# GEMM tile loops: first K iteration peeled with inline-zero SrcC, the 128 per-tile accumulator zeroing moves deleted
# baseline (speedup 1.0000x reference)
; #define STAGE(bufoff, gbase, voff) do { _Pragma("unroll") for (int _i = 0; _i < 2; ++_i) \
;     __builtin_amdgcn_global_load_lds((const unsigned*)((const char*)(gbase) + (voff)[_i]), (LAS unsigned*)(lds + (bufoff) + ldsw + _i * 8192), 16, 0, 0); } while (0)
; #define LDA(dst, b, h) do { _Pragma("unroll") for (int m = 0; m < 4; ++m) _Pragma("unroll") for (int k = 0; k < 2; ++k) dst[m][k] = *(const LAS half8*)(lds + SA(b, h) + aoff + m * 2048 + k * 1024); } while (0)
; #define LDB(dst, b, h) do { _Pragma("unroll") for (int n = 0; n < 2; ++n) _Pragma("unroll") for (int k = 0; k < 2; ++k) dst[n][k] = *(const LAS half8*)(lds + SB(b, h) + boff + n * 2048 + k * 1024); } while (0)
; #define MMA(ai, bj, At_, Bt_) do { __builtin_amdgcn_s_setprio(1); \
;     _Pragma("unroll") for (int m = 0; m < 4; ++m) _Pragma("unroll") for (int n = 0; n < 2; ++n) _Pragma("unroll") for (int k = 0; k < 2; ++k) \
;       acc[ai][bj][m][n] = MFMA16(Bt_[n][k], At_[m][k], acc[ai][bj][m][n]); \
;     __builtin_amdgcn_s_setprio(0); } while (0)
; #define WAIT_V(n) asm volatile("s_waitcnt vmcnt(" #n ")" ::: "memory")
; #define WAIT_L(n) asm volatile("s_waitcnt lgkmcnt(" #n ")" ::: "memory")
; #define BAR __builtin_amdgcn_s_barrier()
; #define SCHED __builtin_amdgcn_sched_barrier(0)
; template <int EPI>
; DI void gemm_phase(const int wid_s, const h16* __restrict__ A, const h16* __restrict__ Bt, const int N, const int K, const EpiArgs ea) {
;     ...
;     for (int t = 0; t < nt; t += 2) {
;       const bool last = (t == nt - 2);
;       const char* a1 = cA + (size_t)(t + 1) * kstep;
;       const char* a2 = last ? nA : cA + (size_t)(t + 2) * kstep; const char* b2 = last ? nB : cB + (size_t)(t + 2) * kstep;
;       const char* a3 = a2 + kstep; const char* b3 = b2 + kstep;
;       LDB(B0, 0, 0); LDB(B1, 0, 1); SCHED; LDA(At, 0, 0); STAGE(SA(1, 1), a1 + hstep, voffA);
;       WAIT_V(8); WAIT_L(0); BAR; MMA(0, 0, At, B0); MMA(0, 1, At, B1); BAR; SCHED;
;       LDA(At, 0, 1); STAGE(SB(0, 0), b2, voffB); STAGE(SB(0, 1), b2 + hstep, voffB); STAGE(SA(0, 0), a2, voffA);
;       WAIT_V(8); WAIT_L(0); BAR; MMA(1, 0, At, B0); MMA(1, 1, At, B1); BAR; SCHED;
.LBB0_121:
	s_mul_i32 s8, s31, 0x1600
	s_mul_hi_i32 s9, s31, 0x1600
	s_add_u32 s8, s28, s8
	s_addc_u32 s9, s29, s9
	s_mul_i32 s10, s38, 0x1600
	v_readlane_b32 s16, v250, 58
	s_mul_hi_i32 s11, s38, 0x1600
	s_add_u32 s41, s16, s10
	v_readlane_b32 s16, v250, 61
	s_addc_u32 s42, s16, s11
	v_readlane_b32 s16, v249, 21
	s_add_u32 s43, s16, s14
	v_readlane_b32 s14, v249, 22
	v_mov_b32_e32 v6, 0
	s_addc_u32 s44, s14, s15
	s_mov_b32 s45, -2
	s_add_u32 s14, s12, 0x100
	s_addc_u32 s15, s13, 0
	s_add_i32 s46, 0, 0x10000
	s_cmp_eq_u32 s45, 40
	s_cselect_b32 s19, s9, s15
	s_cselect_b32 s18, s8, s14
	v_add_u32_e32 v177, s46, v148
	s_cselect_b32 s17, s42, s44
	s_cselect_b32 s16, s41, s43
	s_add_i32 s47, 0, 0x14000
	ds_read_b128 v[144:147], v177
	ds_read_b128 v[152:155], v177 offset:1024
	ds_read_b128 v[178:181], v177 offset:2048
	ds_read_b128 v[182:185], v177 offset:3072
	v_add_u32_e32 v177, s47, v148
	ds_read_b128 v[186:189], v177
	ds_read_b128 v[190:193], v177 offset:1024
	ds_read_b128 v[194:197], v177 offset:2048
	ds_read_b128 v[198:201], v177 offset:3072
	v_lshl_add_u64 v[234:235], s[12:13], 0, v[142:143]
	s_add_i32 m0, s22, 0xc000
	ds_read_b128 v[202:205], v151
	ds_read_b128 v[206:209], v151 offset:1024
	ds_read_b128 v[210:213], v151 offset:2048
	ds_read_b128 v[214:217], v151 offset:3072
	ds_read_b128 v[218:221], v151 offset:4096
	ds_read_b128 v[222:225], v151 offset:5120
	ds_read_b128 v[226:229], v151 offset:6144
	ds_read_b128 v[230:233], v151 offset:7168
	global_load_lds_dwordx4 v[234:235], off
	v_lshl_add_u64 v[234:235], s[12:13], 0, v[140:141]
	s_add_i32 m0, s22, 0xe000
	s_nop 0
	global_load_lds_dwordx4 v[234:235], off
	s_waitcnt vmcnt(8)
	s_waitcnt lgkmcnt(0)
	s_barrier
	s_waitcnt lgkmcnt(0)
	v_mfma_f32_16x16x32_f16 v[130:133], v[144:147], v[202:205], 0
	v_mfma_f32_16x16x32_f16 v[126:129], v[178:181], v[202:205], 0
	v_mfma_f32_16x16x32_f16 v[114:117], v[144:147], v[210:213], 0
	v_mfma_f32_16x16x32_f16 v[110:113], v[178:181], v[210:213], 0
	v_mfma_f32_16x16x32_f16 v[98:101], v[144:147], v[218:221], 0
	v_mfma_f32_16x16x32_f16 v[94:97], v[178:181], v[218:221], 0
	v_mfma_f32_16x16x32_f16 v[82:85], v[144:147], v[226:229], 0
	v_mfma_f32_16x16x32_f16 v[78:81], v[178:181], v[226:229], 0
	v_mfma_f32_16x16x32_f16 v[130:133], v[152:155], v[206:209], v[130:133]
	v_mfma_f32_16x16x32_f16 v[126:129], v[182:185], v[206:209], v[126:129]
	v_mfma_f32_16x16x32_f16 v[114:117], v[152:155], v[214:217], v[114:117]
	v_mfma_f32_16x16x32_f16 v[110:113], v[182:185], v[214:217], v[110:113]
	v_mfma_f32_16x16x32_f16 v[98:101], v[152:155], v[222:225], v[98:101]
	v_mfma_f32_16x16x32_f16 v[94:97], v[182:185], v[222:225], v[94:97]
	v_mfma_f32_16x16x32_f16 v[82:85], v[152:155], v[230:233], v[82:85]
	v_mfma_f32_16x16x32_f16 v[78:81], v[182:185], v[230:233], v[78:81]
	v_mfma_f32_16x16x32_f16 v[122:125], v[186:189], v[202:205], 0
	v_mfma_f32_16x16x32_f16 v[118:121], v[194:197], v[202:205], 0
	v_mfma_f32_16x16x32_f16 v[106:109], v[186:189], v[210:213], 0
	v_mfma_f32_16x16x32_f16 v[102:105], v[194:197], v[210:213], 0
	v_mfma_f32_16x16x32_f16 v[90:93], v[186:189], v[218:221], 0
	v_mfma_f32_16x16x32_f16 v[86:89], v[194:197], v[218:221], 0
	v_mfma_f32_16x16x32_f16 v[74:77], v[186:189], v[226:229], 0
	v_mfma_f32_16x16x32_f16 v[70:73], v[194:197], v[226:229], 0
	v_mfma_f32_16x16x32_f16 v[122:125], v[190:193], v[206:209], v[122:125]
	v_mfma_f32_16x16x32_f16 v[118:121], v[198:201], v[206:209], v[118:121]
	v_mfma_f32_16x16x32_f16 v[106:109], v[190:193], v[214:217], v[106:109]
	v_mfma_f32_16x16x32_f16 v[102:105], v[198:201], v[214:217], v[102:105]
	v_mfma_f32_16x16x32_f16 v[90:93], v[190:193], v[222:225], v[90:93]
	v_mfma_f32_16x16x32_f16 v[86:89], v[198:201], v[222:225], v[86:89]
	v_mfma_f32_16x16x32_f16 v[74:77], v[190:193], v[230:233], v[74:77]
	v_mfma_f32_16x16x32_f16 v[70:73], v[198:201], v[230:233], v[70:73]
	s_barrier
	s_add_i32 s12, s46, s21
	v_lshl_add_u64 v[234:235], s[16:17], 0, v[0:1]
	s_mov_b32 m0, s12
	ds_read_b128 v[202:205], v151 offset:16384
	ds_read_b128 v[206:209], v151 offset:17408
	ds_read_b128 v[210:213], v151 offset:18432
	ds_read_b128 v[214:217], v151 offset:19456
	ds_read_b128 v[218:221], v151 offset:20480
	ds_read_b128 v[222:225], v151 offset:21504
	ds_read_b128 v[226:229], v151 offset:22528
	ds_read_b128 v[230:233], v151 offset:23552
	global_load_lds_dwordx4 v[234:235], off
	s_add_i32 m0, s12, 0x2000
	s_add_u32 s12, s16, 0xb0000
	v_lshl_add_u64 v[236:237], s[16:17], 0, v[138:139]
	s_addc_u32 s13, s17, 0
	s_add_i32 s46, s47, s21
	global_load_lds_dwordx4 v[236:237], off
	v_lshl_add_u64 v[238:239], s[12:13], 0, v[0:1]
	s_mov_b32 m0, s46
	v_lshl_add_u64 v[240:241], s[18:19], 0, v[134:135]
	global_load_lds_dwordx4 v[238:239], off
	v_lshl_add_u64 v[238:239], s[12:13], 0, v[138:139]
	s_add_i32 m0, s46, 0x2000
	s_nop 0
	global_load_lds_dwordx4 v[238:239], off
	v_lshl_add_u64 v[238:239], s[18:19], 0, v[2:3]
	s_mov_b32 m0, s22
	s_nop 0
	global_load_lds_dwordx4 v[238:239], off
	s_mov_b32 m0, s23
	s_nop 0
	global_load_lds_dwordx4 v[240:241], off
	s_waitcnt vmcnt(8)
	s_waitcnt lgkmcnt(0)
	s_barrier
; #define STAGE(bufoff, gbase, voff) do { _Pragma("unroll") for (int _i = 0; _i < 2; ++_i) \
;     __builtin_amdgcn_global_load_lds((const unsigned*)((const char*)(gbase) + (voff)[_i]), (LAS unsigned*)(lds + (bufoff) + ldsw + _i * 8192), 16, 0, 0); } while (0)
; #define LDA(dst, b, h) do { _Pragma("unroll") for (int m = 0; m < 4; ++m) _Pragma("unroll") for (int k = 0; k < 2; ++k) dst[m][k] = *(const LAS half8*)(lds + SA(b, h) + aoff + m * 2048 + k * 1024); } while (0)
; #define LDB(dst, b, h) do { _Pragma("unroll") for (int n = 0; n < 2; ++n) _Pragma("unroll") for (int k = 0; k < 2; ++k) dst[n][k] = *(const LAS half8*)(lds + SB(b, h) + boff + n * 2048 + k * 1024); } while (0)
; #define MMA(ai, bj, At_, Bt_) do { __builtin_amdgcn_s_setprio(1); \
;     _Pragma("unroll") for (int m = 0; m < 4; ++m) _Pragma("unroll") for (int n = 0; n < 2; ++n) _Pragma("unroll") for (int k = 0; k < 2; ++k) \
;       acc[ai][bj][m][n] = MFMA16(Bt_[n][k], At_[m][k], acc[ai][bj][m][n]); \
;     __builtin_amdgcn_s_setprio(0); } while (0)
; #define WAIT_V(n) asm volatile("s_waitcnt vmcnt(" #n ")" ::: "memory")
; #define WAIT_L(n) asm volatile("s_waitcnt lgkmcnt(" #n ")" ::: "memory")
; #define BAR __builtin_amdgcn_s_barrier()
; #define SCHED __builtin_amdgcn_sched_barrier(0)
; template <int EPI>
; DI void gemm_phase(const int wid_s, const h16* __restrict__ A, const h16* __restrict__ Bt, const int N, const int K, const EpiArgs ea) {
;     ...
;       LDB(B0, 0, 0); LDB(B1, 0, 1); SCHED; LDA(At, 0, 0); STAGE(SA(1, 1), a1 + hstep, voffA);
;       WAIT_V(8); WAIT_L(0); BAR; MMA(0, 0, At, B0); MMA(0, 1, At, B1); BAR; SCHED;
;       LDA(At, 0, 1); STAGE(SB(0, 0), b2, voffB); STAGE(SB(0, 1), b2 + hstep, voffB); STAGE(SA(0, 0), a2, voffA);
;       WAIT_V(8); WAIT_L(0); BAR; MMA(1, 0, At, B0); MMA(1, 1, At, B1); BAR; SCHED;
;       LDB(B0, 1, 0); LDB(B1, 1, 1); SCHED; LDA(At, 1, 0); STAGE(SA(0, 1), a2 + hstep, voffA);
;       WAIT_V(8); WAIT_L(0); BAR; MMA(0, 0, At, B0); MMA(0, 1, At, B1); BAR; SCHED;
	s_waitcnt lgkmcnt(0)
	v_mfma_f32_16x16x32_f16 v[66:69], v[144:147], v[202:205], 0
	v_mfma_f32_16x16x32_f16 v[62:65], v[178:181], v[202:205], 0
	v_mfma_f32_16x16x32_f16 v[50:53], v[144:147], v[210:213], 0
	v_mfma_f32_16x16x32_f16 v[46:49], v[178:181], v[210:213], 0
	v_mfma_f32_16x16x32_f16 v[34:37], v[144:147], v[218:221], 0
	v_mfma_f32_16x16x32_f16 v[30:33], v[178:181], v[218:221], 0
	v_mfma_f32_16x16x32_f16 v[18:21], v[144:147], v[226:229], 0
	v_mfma_f32_16x16x32_f16 v[14:17], v[178:181], v[226:229], 0
	v_mfma_f32_16x16x32_f16 v[66:69], v[152:155], v[206:209], v[66:69]
	v_mfma_f32_16x16x32_f16 v[62:65], v[182:185], v[206:209], v[62:65]
	v_mfma_f32_16x16x32_f16 v[50:53], v[152:155], v[214:217], v[50:53]
	v_mfma_f32_16x16x32_f16 v[46:49], v[182:185], v[214:217], v[46:49]
	v_mfma_f32_16x16x32_f16 v[34:37], v[152:155], v[222:225], v[34:37]
	v_mfma_f32_16x16x32_f16 v[30:33], v[182:185], v[222:225], v[30:33]
	v_mfma_f32_16x16x32_f16 v[18:21], v[152:155], v[230:233], v[18:21]
	v_mfma_f32_16x16x32_f16 v[14:17], v[182:185], v[230:233], v[14:17]
	v_mfma_f32_16x16x32_f16 v[58:61], v[186:189], v[202:205], 0
	v_mfma_f32_16x16x32_f16 v[54:57], v[194:197], v[202:205], 0
	v_mfma_f32_16x16x32_f16 v[42:45], v[186:189], v[210:213], 0
	v_mfma_f32_16x16x32_f16 v[38:41], v[194:197], v[210:213], 0
	v_mfma_f32_16x16x32_f16 v[26:29], v[186:189], v[218:221], 0
	v_mfma_f32_16x16x32_f16 v[22:25], v[194:197], v[218:221], 0
	v_mfma_f32_16x16x32_f16 v[10:13], v[186:189], v[226:229], 0
	v_mfma_f32_16x16x32_f16 v[6:9], v[194:197], v[226:229], 0
	v_mfma_f32_16x16x32_f16 v[58:61], v[190:193], v[206:209], v[58:61]
	v_mfma_f32_16x16x32_f16 v[54:57], v[198:201], v[206:209], v[54:57]
	v_mfma_f32_16x16x32_f16 v[42:45], v[190:193], v[214:217], v[42:45]
	v_mfma_f32_16x16x32_f16 v[38:41], v[198:201], v[214:217], v[38:41]
	v_mfma_f32_16x16x32_f16 v[26:29], v[190:193], v[222:225], v[26:29]
	v_mfma_f32_16x16x32_f16 v[22:25], v[198:201], v[222:225], v[22:25]
	v_mfma_f32_16x16x32_f16 v[10:13], v[190:193], v[230:233], v[10:13]
	v_mfma_f32_16x16x32_f16 v[6:9], v[198:201], v[230:233], v[6:9]
	s_barrier
	s_add_i32 s46, 0, 0x18000
	v_add_u32_e32 v177, s46, v148
	s_add_i32 s47, 0, 0x1c000
	ds_read_b128 v[144:147], v177
	ds_read_b128 v[152:155], v177 offset:1024
	ds_read_b128 v[178:181], v177 offset:2048
	ds_read_b128 v[182:185], v177 offset:3072
	v_add_u32_e32 v177, s47, v148
	ds_read_b128 v[186:189], v177
	ds_read_b128 v[190:193], v177 offset:1024
	ds_read_b128 v[194:197], v177 offset:2048
	ds_read_b128 v[198:201], v177 offset:3072
	s_add_u32 s12, s18, 0xb0000
	s_addc_u32 s13, s19, 0
	s_mov_b32 m0, s24
	v_lshl_add_u64 v[242:243], s[12:13], 0, v[2:3]
	ds_read_b128 v[202:205], v151 offset:32768
	ds_read_b128 v[206:209], v151 offset:33792
	ds_read_b128 v[210:213], v151 offset:34816
	ds_read_b128 v[214:217], v151 offset:35840
	ds_read_b128 v[218:221], v151 offset:36864
	ds_read_b128 v[222:225], v151 offset:37888
	ds_read_b128 v[226:229], v151 offset:38912
	ds_read_b128 v[230:233], v151 offset:39936
	global_load_lds_dwordx4 v[242:243], off
	v_lshl_add_u64 v[242:243], s[12:13], 0, v[134:135]
	s_mov_b32 m0, s26
	s_nop 0
	global_load_lds_dwordx4 v[242:243], off
	s_waitcnt vmcnt(8)
	s_waitcnt lgkmcnt(0)
	s_barrier
	s_waitcnt lgkmcnt(0)
	v_mfma_f32_16x16x32_f16 v[130:133], v[144:147], v[202:205], v[130:133]
	v_mfma_f32_16x16x32_f16 v[126:129], v[178:181], v[202:205], v[126:129]
	v_mfma_f32_16x16x32_f16 v[114:117], v[144:147], v[210:213], v[114:117]
	v_mfma_f32_16x16x32_f16 v[110:113], v[178:181], v[210:213], v[110:113]
	v_mfma_f32_16x16x32_f16 v[98:101], v[144:147], v[218:221], v[98:101]
	v_mfma_f32_16x16x32_f16 v[94:97], v[178:181], v[218:221], v[94:97]
	v_mfma_f32_16x16x32_f16 v[82:85], v[144:147], v[226:229], v[82:85]
	v_mfma_f32_16x16x32_f16 v[78:81], v[178:181], v[226:229], v[78:81]
	v_mfma_f32_16x16x32_f16 v[130:133], v[152:155], v[206:209], v[130:133]
	v_mfma_f32_16x16x32_f16 v[126:129], v[182:185], v[206:209], v[126:129]
	v_mfma_f32_16x16x32_f16 v[114:117], v[152:155], v[214:217], v[114:117]
	v_mfma_f32_16x16x32_f16 v[110:113], v[182:185], v[214:217], v[110:113]
	v_mfma_f32_16x16x32_f16 v[98:101], v[152:155], v[222:225], v[98:101]
	v_mfma_f32_16x16x32_f16 v[94:97], v[182:185], v[222:225], v[94:97]
	v_mfma_f32_16x16x32_f16 v[82:85], v[152:155], v[230:233], v[82:85]
	v_mfma_f32_16x16x32_f16 v[78:81], v[182:185], v[230:233], v[78:81]
	v_mfma_f32_16x16x32_f16 v[122:125], v[186:189], v[202:205], v[122:125]
	v_mfma_f32_16x16x32_f16 v[118:121], v[194:197], v[202:205], v[118:121]
	v_mfma_f32_16x16x32_f16 v[106:109], v[186:189], v[210:213], v[106:109]
	v_mfma_f32_16x16x32_f16 v[102:105], v[194:197], v[210:213], v[102:105]
	v_mfma_f32_16x16x32_f16 v[90:93], v[186:189], v[218:221], v[90:93]
	v_mfma_f32_16x16x32_f16 v[86:89], v[194:197], v[218:221], v[86:89]
	v_mfma_f32_16x16x32_f16 v[74:77], v[186:189], v[226:229], v[74:77]
	v_mfma_f32_16x16x32_f16 v[70:73], v[194:197], v[226:229], v[70:73]
	v_mfma_f32_16x16x32_f16 v[122:125], v[190:193], v[206:209], v[122:125]
	v_mfma_f32_16x16x32_f16 v[118:121], v[198:201], v[206:209], v[118:121]
	v_mfma_f32_16x16x32_f16 v[106:109], v[190:193], v[214:217], v[106:109]
	v_mfma_f32_16x16x32_f16 v[102:105], v[198:201], v[214:217], v[102:105]
	v_mfma_f32_16x16x32_f16 v[90:93], v[190:193], v[222:225], v[90:93]
	v_mfma_f32_16x16x32_f16 v[86:89], v[198:201], v[222:225], v[86:89]
	v_mfma_f32_16x16x32_f16 v[74:77], v[190:193], v[230:233], v[74:77]
	v_mfma_f32_16x16x32_f16 v[70:73], v[198:201], v[230:233], v[70:73]
	s_barrier
; #define STAGE(bufoff, gbase, voff) do { _Pragma("unroll") for (int _i = 0; _i < 2; ++_i) \
;     __builtin_amdgcn_global_load_lds((const unsigned*)((const char*)(gbase) + (voff)[_i]), (LAS unsigned*)(lds + (bufoff) + ldsw + _i * 8192), 16, 0, 0); } while (0)
; #define LDA(dst, b, h) do { _Pragma("unroll") for (int m = 0; m < 4; ++m) _Pragma("unroll") for (int k = 0; k < 2; ++k) dst[m][k] = *(const LAS half8*)(lds + SA(b, h) + aoff + m * 2048 + k * 1024); } while (0)
; #define LDB(dst, b, h) do { _Pragma("unroll") for (int n = 0; n < 2; ++n) _Pragma("unroll") for (int k = 0; k < 2; ++k) dst[n][k] = *(const LAS half8*)(lds + SB(b, h) + boff + n * 2048 + k * 1024); } while (0)
; #define MMA(ai, bj, At_, Bt_) do { __builtin_amdgcn_s_setprio(1); \
;     _Pragma("unroll") for (int m = 0; m < 4; ++m) _Pragma("unroll") for (int n = 0; n < 2; ++n) _Pragma("unroll") for (int k = 0; k < 2; ++k) \
;       acc[ai][bj][m][n] = MFMA16(Bt_[n][k], At_[m][k], acc[ai][bj][m][n]); \
;     __builtin_amdgcn_s_setprio(0); } while (0)
; #define WAIT_V(n) asm volatile("s_waitcnt vmcnt(" #n ")" ::: "memory")
; #define BAR __builtin_amdgcn_s_barrier()
; template <int EPI>
; DI void gemm_phase(const int wid_s, const h16* __restrict__ A, const h16* __restrict__ Bt, const int N, const int K, const EpiArgs ea) {
;     ...
;     for (int t = 0; t < nt; t += 2) {
;       const bool last = (t == nt - 2);
;       const char* a1 = cA + (size_t)(t + 1) * kstep;
;       const char* a2 = last ? nA : cA + (size_t)(t + 2) * kstep; const char* b2 = last ? nB : cB + (size_t)(t + 2) * kstep;
;       const char* a3 = a2 + kstep; const char* b3 = b2 + kstep;
;       LDB(B0, 0, 0); LDB(B1, 0, 1); SCHED; LDA(At, 0, 0); STAGE(SA(1, 1), a1 + hstep, voffA);
;       WAIT_V(8); WAIT_L(0); BAR; MMA(0, 0, At, B0); MMA(0, 1, At, B1); BAR; SCHED;
;       LDA(At, 0, 1); STAGE(SB(0, 0), b2, voffB); STAGE(SB(0, 1), b2 + hstep, voffB); STAGE(SA(0, 0), a2, voffA);
;       WAIT_V(8); WAIT_L(0); BAR; MMA(1, 0, At, B0); MMA(1, 1, At, B1); BAR; SCHED;
;       LDB(B0, 1, 0); LDB(B1, 1, 1); SCHED; LDA(At, 1, 0); STAGE(SA(0, 1), a2 + hstep, voffA);
;       WAIT_V(8); WAIT_L(0); BAR; MMA(0, 0, At, B0); MMA(0, 1, At, B1); BAR; SCHED;
;       LDA(At, 1, 1); STAGE(SB(1, 0), b3, voffB); STAGE(SB(1, 1), b3 + hstep, voffB); STAGE(SA(1, 0), a3, voffA);
;       WAIT_V(8); WAIT_L(0); BAR; MMA(1, 0, At, B0); MMA(1, 1, At, B1); BAR; SCHED;
	s_add_i32 s12, s46, s21
	v_lshl_add_u64 v[234:235], v[234:235], 0, s[36:37]
	s_mov_b32 m0, s12
	ds_read_b128 v[202:205], v151 offset:49152
	ds_read_b128 v[206:209], v151 offset:50176
	ds_read_b128 v[210:213], v151 offset:51200
	ds_read_b128 v[214:217], v151 offset:52224
	ds_read_b128 v[218:221], v151 offset:53248
	ds_read_b128 v[222:225], v151 offset:54272
	ds_read_b128 v[226:229], v151 offset:55296
	ds_read_b128 v[230:233], v151 offset:56320
	global_load_lds_dwordx4 v[234:235], off
	s_add_i32 m0, s12, 0x2000
	s_add_u32 s12, s16, 0xb0080
	v_lshl_add_u64 v[234:235], v[236:237], 0, s[36:37]
	s_addc_u32 s13, s17, 0
	s_add_i32 s16, s47, s21
	global_load_lds_dwordx4 v[234:235], off
	v_lshl_add_u64 v[234:235], s[12:13], 0, v[0:1]
	s_mov_b32 m0, s16
	s_nop 0
	global_load_lds_dwordx4 v[234:235], off
	v_lshl_add_u64 v[234:235], s[12:13], 0, v[138:139]
	s_add_i32 m0, s16, 0x2000
	s_nop 0
	global_load_lds_dwordx4 v[234:235], off
	v_lshl_add_u64 v[234:235], v[238:239], 0, s[36:37]
	s_mov_b32 m0, s27
	s_nop 0
	global_load_lds_dwordx4 v[234:235], off
	v_lshl_add_u64 v[234:235], v[240:241], 0, s[36:37]
	s_mov_b32 m0, s30
	s_nop 0
	global_load_lds_dwordx4 v[234:235], off
	s_waitcnt vmcnt(8)
	s_waitcnt lgkmcnt(0)
	s_barrier
	s_waitcnt lgkmcnt(0)
	v_mfma_f32_16x16x32_f16 v[66:69], v[144:147], v[202:205], v[66:69]
	v_mfma_f32_16x16x32_f16 v[62:65], v[178:181], v[202:205], v[62:65]
	v_mfma_f32_16x16x32_f16 v[50:53], v[144:147], v[210:213], v[50:53]
	v_mfma_f32_16x16x32_f16 v[46:49], v[178:181], v[210:213], v[46:49]
	v_mfma_f32_16x16x32_f16 v[34:37], v[144:147], v[218:221], v[34:37]
	v_mfma_f32_16x16x32_f16 v[30:33], v[178:181], v[218:221], v[30:33]
	v_mfma_f32_16x16x32_f16 v[18:21], v[144:147], v[226:229], v[18:21]
	v_mfma_f32_16x16x32_f16 v[14:17], v[178:181], v[226:229], v[14:17]
	v_mfma_f32_16x16x32_f16 v[66:69], v[152:155], v[206:209], v[66:69]
	v_mfma_f32_16x16x32_f16 v[62:65], v[182:185], v[206:209], v[62:65]
	v_mfma_f32_16x16x32_f16 v[50:53], v[152:155], v[214:217], v[50:53]
	v_mfma_f32_16x16x32_f16 v[46:49], v[182:185], v[214:217], v[46:49]
	v_mfma_f32_16x16x32_f16 v[34:37], v[152:155], v[222:225], v[34:37]
	v_mfma_f32_16x16x32_f16 v[30:33], v[182:185], v[222:225], v[30:33]
	v_mfma_f32_16x16x32_f16 v[18:21], v[152:155], v[230:233], v[18:21]
	v_mfma_f32_16x16x32_f16 v[14:17], v[182:185], v[230:233], v[14:17]
	v_mfma_f32_16x16x32_f16 v[58:61], v[186:189], v[202:205], v[58:61]
	v_mfma_f32_16x16x32_f16 v[54:57], v[194:197], v[202:205], v[54:57]
	v_mfma_f32_16x16x32_f16 v[42:45], v[186:189], v[210:213], v[42:45]
	v_mfma_f32_16x16x32_f16 v[38:41], v[194:197], v[210:213], v[38:41]
	v_mfma_f32_16x16x32_f16 v[26:29], v[186:189], v[218:221], v[26:29]
	v_mfma_f32_16x16x32_f16 v[22:25], v[194:197], v[218:221], v[22:25]
	v_mfma_f32_16x16x32_f16 v[10:13], v[186:189], v[226:229], v[10:13]
	v_mfma_f32_16x16x32_f16 v[6:9], v[194:197], v[226:229], v[6:9]
	v_mfma_f32_16x16x32_f16 v[58:61], v[190:193], v[206:209], v[58:61]
	v_mfma_f32_16x16x32_f16 v[54:57], v[198:201], v[206:209], v[54:57]
	v_mfma_f32_16x16x32_f16 v[42:45], v[190:193], v[214:217], v[42:45]
	v_mfma_f32_16x16x32_f16 v[38:41], v[198:201], v[214:217], v[38:41]
	v_mfma_f32_16x16x32_f16 v[26:29], v[190:193], v[222:225], v[26:29]
	v_mfma_f32_16x16x32_f16 v[22:25], v[198:201], v[222:225], v[22:25]
	v_mfma_f32_16x16x32_f16 v[10:13], v[190:193], v[230:233], v[10:13]
	v_mfma_f32_16x16x32_f16 v[6:9], v[198:201], v[230:233], v[6:9]
	s_barrier
	s_add_i32 s45, s45, 2
	s_add_u32 s43, s43, 0x100
	s_addc_u32 s44, s44, 0
	s_cmp_gt_u32 s45, 41
	s_mov_b64 s[12:13], s[14:15]

; #define STAGE(bufoff, gbase, voff) do { _Pragma("unroll") for (int _i = 0; _i < 2; ++_i) \
;     __builtin_amdgcn_global_load_lds((const unsigned*)((const char*)(gbase) + (voff)[_i]), (LAS unsigned*)(lds + (bufoff) + ldsw + _i * 8192), 16, 0, 0); } while (0)
; #define LDA(dst, b, h) do { _Pragma("unroll") for (int m = 0; m < 4; ++m) _Pragma("unroll") for (int k = 0; k < 2; ++k) dst[m][k] = *(const LAS half8*)(lds + SA(b, h) + aoff + m * 2048 + k * 1024); } while (0)
; #define LDB(dst, b, h) do { _Pragma("unroll") for (int n = 0; n < 2; ++n) _Pragma("unroll") for (int k = 0; k < 2; ++k) dst[n][k] = *(const LAS half8*)(lds + SB(b, h) + boff + n * 2048 + k * 1024); } while (0)
; #define MMA(ai, bj, At_, Bt_) do { __builtin_amdgcn_s_setprio(1); \
;     _Pragma("unroll") for (int m = 0; m < 4; ++m) _Pragma("unroll") for (int n = 0; n < 2; ++n) _Pragma("unroll") for (int k = 0; k < 2; ++k) \
;       acc[ai][bj][m][n] = MFMA16(Bt_[n][k], At_[m][k], acc[ai][bj][m][n]); \
;     __builtin_amdgcn_s_setprio(0); } while (0)
; #define WAIT_V(n) asm volatile("s_waitcnt vmcnt(" #n ")" ::: "memory")
; #define WAIT_L(n) asm volatile("s_waitcnt lgkmcnt(" #n ")" ::: "memory")
; #define BAR __builtin_amdgcn_s_barrier()
; #define SCHED __builtin_amdgcn_sched_barrier(0)
; template <int EPI>
; DI void gemm_phase(const int wid_s, const h16* __restrict__ A, const h16* __restrict__ Bt, const int N, const int K, const EpiArgs ea) {
;     ...
;     int nbrow = brow, nbcol = bcol;
;     if (has_next) TILE_RC(Ln, nbrow, nbcol);
;     const char* nA = (const char*)A + (size_t)nbrow * K * 2;
;     const char* nB = (const char*)Bt + (size_t)nbcol * K * 2;
;     for (int t = 0; t < nt; t += 2) {
;       const bool last = (t == nt - 2);
;       const char* a1 = cA + (size_t)(t + 1) * kstep;
;       const char* a2 = last ? nA : cA + (size_t)(t + 2) * kstep; const char* b2 = last ? nB : cB + (size_t)(t + 2) * kstep;
;       const char* a3 = a2 + kstep; const char* b3 = b2 + kstep;
;       LDB(B0, 0, 0); LDB(B1, 0, 1); SCHED; LDA(At, 0, 0); STAGE(SA(1, 1), a1 + hstep, voffA);
;       WAIT_V(8); WAIT_L(0); BAR; MMA(0, 0, At, B0); MMA(0, 1, At, B1); BAR; SCHED;
;       LDA(At, 0, 1); STAGE(SB(0, 0), b2, voffB); STAGE(SB(0, 1), b2 + hstep, voffB); STAGE(SA(0, 0), a2, voffA);
;       WAIT_V(8); WAIT_L(0); BAR; MMA(1, 0, At, B0); MMA(1, 1, At, B1); BAR; SCHED;
.LBB0_140:
	s_ashr_i32 s9, s8, 31
	s_lshl_b64 s[12:13], s[8:9], 11
	s_add_u32 s9, s92, s12
	s_addc_u32 s42, s93, s13
	s_ashr_i32 s11, s10, 31
	s_lshl_b64 s[14:15], s[10:11], 11
	v_readlane_b32 s11, v250, 62
	s_add_u32 s11, s11, s14
	v_readlane_b32 s26, v249, 1
	s_addc_u32 s43, s26, s15
	v_readlane_b32 s26, v249, 23
	s_add_u32 s44, s26, s22
	v_readlane_b32 s22, v249, 24
	s_addc_u32 s45, s22, s23
	s_add_u32 s46, s86, s20
	v_mov_b32_e32 v6, 0
	v_lshl_add_u64 v[144:145], v[140:141], 0, s[20:21]
	v_lshl_add_u64 v[146:147], v[142:143], 0, s[20:21]
	s_addc_u32 s47, s87, s21
	s_mov_b32 s48, -2
	s_mov_b64 s[20:21], 0
	s_add_u32 s22, s46, s20
	s_addc_u32 s23, s47, s21
	s_add_u32 s22, s22, 0x520e100
	s_addc_u32 s23, s23, 0
	s_add_u32 s49, s44, s20
	s_addc_u32 s50, s45, s21
	s_add_i32 s51, 0, 0x10000
	s_cmpk_eq_i32 s20, 0x700
	s_cselect_b32 s27, s42, s23
	s_cselect_b32 s26, s9, s22
	v_add_u32_e32 v177, s51, v148
	s_cselect_b32 s23, s43, s50
	s_cselect_b32 s22, s11, s49
	s_add_i32 s49, 0, 0x14000
	ds_read_b128 v[152:155], v177
	ds_read_b128 v[178:181], v177 offset:1024
	ds_read_b128 v[182:185], v177 offset:2048
	ds_read_b128 v[186:189], v177 offset:3072
	v_add_u32_e32 v177, s49, v148
	ds_read_b128 v[190:193], v177
	ds_read_b128 v[194:197], v177 offset:1024
	ds_read_b128 v[198:201], v177 offset:2048
	ds_read_b128 v[202:205], v177 offset:3072
	v_lshl_add_u64 v[238:239], v[146:147], 0, s[20:21]
	s_add_i32 m0, s17, 0xc000
	ds_read_b128 v[206:209], v151
	ds_read_b128 v[210:213], v151 offset:1024
	ds_read_b128 v[214:217], v151 offset:2048
	ds_read_b128 v[218:221], v151 offset:3072
	ds_read_b128 v[222:225], v151 offset:4096
	ds_read_b128 v[226:229], v151 offset:5120
	ds_read_b128 v[230:233], v151 offset:6144
	ds_read_b128 v[234:237], v151 offset:7168
	global_load_lds_dwordx4 v[238:239], off
	v_lshl_add_u64 v[238:239], v[144:145], 0, s[20:21]
	s_add_i32 m0, s17, 0xe000
	s_nop 0
	global_load_lds_dwordx4 v[238:239], off
	s_waitcnt vmcnt(8)
	s_waitcnt lgkmcnt(0)
	s_barrier
	s_waitcnt lgkmcnt(0)
	v_mfma_f32_16x16x32_f16 v[130:133], v[152:155], v[206:209], 0
	v_mfma_f32_16x16x32_f16 v[126:129], v[182:185], v[206:209], 0
	v_mfma_f32_16x16x32_f16 v[114:117], v[152:155], v[214:217], 0
	v_mfma_f32_16x16x32_f16 v[110:113], v[182:185], v[214:217], 0
	v_mfma_f32_16x16x32_f16 v[98:101], v[152:155], v[222:225], 0
	v_mfma_f32_16x16x32_f16 v[94:97], v[182:185], v[222:225], 0
	v_mfma_f32_16x16x32_f16 v[82:85], v[152:155], v[230:233], 0
	v_mfma_f32_16x16x32_f16 v[78:81], v[182:185], v[230:233], 0
	v_mfma_f32_16x16x32_f16 v[130:133], v[178:181], v[210:213], v[130:133]
	v_mfma_f32_16x16x32_f16 v[126:129], v[186:189], v[210:213], v[126:129]
	v_mfma_f32_16x16x32_f16 v[114:117], v[178:181], v[218:221], v[114:117]
	v_mfma_f32_16x16x32_f16 v[110:113], v[186:189], v[218:221], v[110:113]
	v_mfma_f32_16x16x32_f16 v[98:101], v[178:181], v[226:229], v[98:101]
	v_mfma_f32_16x16x32_f16 v[94:97], v[186:189], v[226:229], v[94:97]
	v_mfma_f32_16x16x32_f16 v[82:85], v[178:181], v[234:237], v[82:85]
	v_mfma_f32_16x16x32_f16 v[78:81], v[186:189], v[234:237], v[78:81]
	v_mfma_f32_16x16x32_f16 v[122:125], v[190:193], v[206:209], 0
	v_mfma_f32_16x16x32_f16 v[118:121], v[198:201], v[206:209], 0
	v_mfma_f32_16x16x32_f16 v[106:109], v[190:193], v[214:217], 0
	v_mfma_f32_16x16x32_f16 v[102:105], v[198:201], v[214:217], 0
	v_mfma_f32_16x16x32_f16 v[90:93], v[190:193], v[222:225], 0
	v_mfma_f32_16x16x32_f16 v[86:89], v[198:201], v[222:225], 0
	v_mfma_f32_16x16x32_f16 v[74:77], v[190:193], v[230:233], 0
	v_mfma_f32_16x16x32_f16 v[70:73], v[198:201], v[230:233], 0
	v_mfma_f32_16x16x32_f16 v[122:125], v[194:197], v[210:213], v[122:125]
	v_mfma_f32_16x16x32_f16 v[118:121], v[202:205], v[210:213], v[118:121]
	v_mfma_f32_16x16x32_f16 v[106:109], v[194:197], v[218:221], v[106:109]
	v_mfma_f32_16x16x32_f16 v[102:105], v[202:205], v[218:221], v[102:105]
	v_mfma_f32_16x16x32_f16 v[90:93], v[194:197], v[226:229], v[90:93]
	v_mfma_f32_16x16x32_f16 v[86:89], v[202:205], v[226:229], v[86:89]
	v_mfma_f32_16x16x32_f16 v[74:77], v[194:197], v[234:237], v[74:77]
	v_mfma_f32_16x16x32_f16 v[70:73], v[202:205], v[234:237], v[70:73]
	s_barrier
	s_add_i32 s50, s51, s30
	v_lshl_add_u64 v[238:239], s[22:23], 0, v[0:1]
	s_mov_b32 m0, s50
	ds_read_b128 v[206:209], v151 offset:16384
	ds_read_b128 v[210:213], v151 offset:17408
	ds_read_b128 v[214:217], v151 offset:18432
	ds_read_b128 v[218:221], v151 offset:19456
	ds_read_b128 v[222:225], v151 offset:20480
	ds_read_b128 v[226:229], v151 offset:21504
	ds_read_b128 v[230:233], v151 offset:22528
	ds_read_b128 v[234:237], v151 offset:23552
	global_load_lds_dwordx4 v[238:239], off
	s_add_i32 m0, s50, 0x2000
	s_add_u32 s50, s22, 0x40000
	v_lshl_add_u64 v[240:241], s[22:23], 0, v[2:3]
	s_addc_u32 s51, s23, 0
	s_add_i32 s49, s49, s30
	global_load_lds_dwordx4 v[240:241], off
	v_lshl_add_u64 v[242:243], s[50:51], 0, v[0:1]
	s_mov_b32 m0, s49
	v_lshl_add_u64 v[244:245], s[26:27], 0, v[134:135]
	global_load_lds_dwordx4 v[242:243], off
	v_lshl_add_u64 v[242:243], s[50:51], 0, v[2:3]
	s_add_i32 m0, s49, 0x2000
	s_nop 0
	global_load_lds_dwordx4 v[242:243], off
	v_lshl_add_u64 v[242:243], s[26:27], 0, v[138:139]
	s_mov_b32 m0, s17
	s_nop 0
	global_load_lds_dwordx4 v[242:243], off
	s_mov_b32 m0, s19
	s_nop 0
	global_load_lds_dwordx4 v[244:245], off
	s_waitcnt vmcnt(8)
	s_waitcnt lgkmcnt(0)
	s_barrier
; #define STAGE(bufoff, gbase, voff) do { _Pragma("unroll") for (int _i = 0; _i < 2; ++_i) \
;     __builtin_amdgcn_global_load_lds((const unsigned*)((const char*)(gbase) + (voff)[_i]), (LAS unsigned*)(lds + (bufoff) + ldsw + _i * 8192), 16, 0, 0); } while (0)
; #define LDA(dst, b, h) do { _Pragma("unroll") for (int m = 0; m < 4; ++m) _Pragma("unroll") for (int k = 0; k < 2; ++k) dst[m][k] = *(const LAS half8*)(lds + SA(b, h) + aoff + m * 2048 + k * 1024); } while (0)
; #define LDB(dst, b, h) do { _Pragma("unroll") for (int n = 0; n < 2; ++n) _Pragma("unroll") for (int k = 0; k < 2; ++k) dst[n][k] = *(const LAS half8*)(lds + SB(b, h) + boff + n * 2048 + k * 1024); } while (0)
; #define MMA(ai, bj, At_, Bt_) do { __builtin_amdgcn_s_setprio(1); \
;     _Pragma("unroll") for (int m = 0; m < 4; ++m) _Pragma("unroll") for (int n = 0; n < 2; ++n) _Pragma("unroll") for (int k = 0; k < 2; ++k) \
;       acc[ai][bj][m][n] = MFMA16(Bt_[n][k], At_[m][k], acc[ai][bj][m][n]); \
;     __builtin_amdgcn_s_setprio(0); } while (0)
; #define WAIT_V(n) asm volatile("s_waitcnt vmcnt(" #n ")" ::: "memory")
; #define WAIT_L(n) asm volatile("s_waitcnt lgkmcnt(" #n ")" ::: "memory")
; #define BAR __builtin_amdgcn_s_barrier()
; #define SCHED __builtin_amdgcn_sched_barrier(0)
; template <int EPI>
; DI void gemm_phase(const int wid_s, const h16* __restrict__ A, const h16* __restrict__ Bt, const int N, const int K, const EpiArgs ea) {
;     ...
;       LDB(B0, 0, 0); LDB(B1, 0, 1); SCHED; LDA(At, 0, 0); STAGE(SA(1, 1), a1 + hstep, voffA);
;       WAIT_V(8); WAIT_L(0); BAR; MMA(0, 0, At, B0); MMA(0, 1, At, B1); BAR; SCHED;
;       LDA(At, 0, 1); STAGE(SB(0, 0), b2, voffB); STAGE(SB(0, 1), b2 + hstep, voffB); STAGE(SA(0, 0), a2, voffA);
;       WAIT_V(8); WAIT_L(0); BAR; MMA(1, 0, At, B0); MMA(1, 1, At, B1); BAR; SCHED;
;       LDB(B0, 1, 0); LDB(B1, 1, 1); SCHED; LDA(At, 1, 0); STAGE(SA(0, 1), a2 + hstep, voffA);
;       WAIT_V(8); WAIT_L(0); BAR; MMA(0, 0, At, B0); MMA(0, 1, At, B1); BAR; SCHED;
	s_waitcnt lgkmcnt(0)
	v_mfma_f32_16x16x32_f16 v[66:69], v[152:155], v[206:209], 0
	v_mfma_f32_16x16x32_f16 v[62:65], v[182:185], v[206:209], 0
	v_mfma_f32_16x16x32_f16 v[50:53], v[152:155], v[214:217], 0
	v_mfma_f32_16x16x32_f16 v[46:49], v[182:185], v[214:217], 0
	v_mfma_f32_16x16x32_f16 v[34:37], v[152:155], v[222:225], 0
	v_mfma_f32_16x16x32_f16 v[30:33], v[182:185], v[222:225], 0
	v_mfma_f32_16x16x32_f16 v[18:21], v[152:155], v[230:233], 0
	v_mfma_f32_16x16x32_f16 v[14:17], v[182:185], v[230:233], 0
	v_mfma_f32_16x16x32_f16 v[66:69], v[178:181], v[210:213], v[66:69]
	v_mfma_f32_16x16x32_f16 v[62:65], v[186:189], v[210:213], v[62:65]
	v_mfma_f32_16x16x32_f16 v[50:53], v[178:181], v[218:221], v[50:53]
	v_mfma_f32_16x16x32_f16 v[46:49], v[186:189], v[218:221], v[46:49]
	v_mfma_f32_16x16x32_f16 v[34:37], v[178:181], v[226:229], v[34:37]
	v_mfma_f32_16x16x32_f16 v[30:33], v[186:189], v[226:229], v[30:33]
	v_mfma_f32_16x16x32_f16 v[18:21], v[178:181], v[234:237], v[18:21]
	v_mfma_f32_16x16x32_f16 v[14:17], v[186:189], v[234:237], v[14:17]
	v_mfma_f32_16x16x32_f16 v[58:61], v[190:193], v[206:209], 0
	v_mfma_f32_16x16x32_f16 v[54:57], v[198:201], v[206:209], 0
	v_mfma_f32_16x16x32_f16 v[42:45], v[190:193], v[214:217], 0
	v_mfma_f32_16x16x32_f16 v[38:41], v[198:201], v[214:217], 0
	v_mfma_f32_16x16x32_f16 v[26:29], v[190:193], v[222:225], 0
	v_mfma_f32_16x16x32_f16 v[22:25], v[198:201], v[222:225], 0
	v_mfma_f32_16x16x32_f16 v[10:13], v[190:193], v[230:233], 0
	v_mfma_f32_16x16x32_f16 v[6:9], v[198:201], v[230:233], 0
	v_mfma_f32_16x16x32_f16 v[58:61], v[194:197], v[210:213], v[58:61]
	v_mfma_f32_16x16x32_f16 v[54:57], v[202:205], v[210:213], v[54:57]
	v_mfma_f32_16x16x32_f16 v[42:45], v[194:197], v[218:221], v[42:45]
	v_mfma_f32_16x16x32_f16 v[38:41], v[202:205], v[218:221], v[38:41]
	v_mfma_f32_16x16x32_f16 v[26:29], v[194:197], v[226:229], v[26:29]
	v_mfma_f32_16x16x32_f16 v[22:25], v[202:205], v[226:229], v[22:25]
	v_mfma_f32_16x16x32_f16 v[10:13], v[194:197], v[234:237], v[10:13]
	v_mfma_f32_16x16x32_f16 v[6:9], v[202:205], v[234:237], v[6:9]
	s_barrier
	s_add_i32 s49, 0, 0x18000
	v_add_u32_e32 v177, s49, v148
	s_add_i32 s50, 0, 0x1c000
	ds_read_b128 v[152:155], v177
	ds_read_b128 v[178:181], v177 offset:1024
	ds_read_b128 v[182:185], v177 offset:2048
	ds_read_b128 v[186:189], v177 offset:3072
	v_add_u32_e32 v177, s50, v148
	ds_read_b128 v[190:193], v177
	ds_read_b128 v[194:197], v177 offset:1024
	ds_read_b128 v[198:201], v177 offset:2048
	ds_read_b128 v[202:205], v177 offset:3072
	s_add_u32 s26, s26, 0x40000
	s_addc_u32 s27, s27, 0
	s_mov_b32 m0, s31
	v_lshl_add_u64 v[246:247], s[26:27], 0, v[138:139]
	ds_read_b128 v[206:209], v151 offset:32768
	ds_read_b128 v[210:213], v151 offset:33792
	ds_read_b128 v[214:217], v151 offset:34816
	ds_read_b128 v[218:221], v151 offset:35840
	ds_read_b128 v[222:225], v151 offset:36864
	ds_read_b128 v[226:229], v151 offset:37888
	ds_read_b128 v[230:233], v151 offset:38912
	ds_read_b128 v[234:237], v151 offset:39936
	global_load_lds_dwordx4 v[246:247], off
	v_lshl_add_u64 v[246:247], s[26:27], 0, v[134:135]
	s_mov_b32 m0, s38
	s_nop 0
	global_load_lds_dwordx4 v[246:247], off
	s_waitcnt vmcnt(8)
	s_waitcnt lgkmcnt(0)
	s_barrier
	s_waitcnt lgkmcnt(0)
	v_mfma_f32_16x16x32_f16 v[130:133], v[152:155], v[206:209], v[130:133]
	v_mfma_f32_16x16x32_f16 v[126:129], v[182:185], v[206:209], v[126:129]
	v_mfma_f32_16x16x32_f16 v[114:117], v[152:155], v[214:217], v[114:117]
	v_mfma_f32_16x16x32_f16 v[110:113], v[182:185], v[214:217], v[110:113]
	v_mfma_f32_16x16x32_f16 v[98:101], v[152:155], v[222:225], v[98:101]
	v_mfma_f32_16x16x32_f16 v[94:97], v[182:185], v[222:225], v[94:97]
	v_mfma_f32_16x16x32_f16 v[82:85], v[152:155], v[230:233], v[82:85]
	v_mfma_f32_16x16x32_f16 v[78:81], v[182:185], v[230:233], v[78:81]
	v_mfma_f32_16x16x32_f16 v[130:133], v[178:181], v[210:213], v[130:133]
	v_mfma_f32_16x16x32_f16 v[126:129], v[186:189], v[210:213], v[126:129]
	v_mfma_f32_16x16x32_f16 v[114:117], v[178:181], v[218:221], v[114:117]
	v_mfma_f32_16x16x32_f16 v[110:113], v[186:189], v[218:221], v[110:113]
	v_mfma_f32_16x16x32_f16 v[98:101], v[178:181], v[226:229], v[98:101]
	v_mfma_f32_16x16x32_f16 v[94:97], v[186:189], v[226:229], v[94:97]
	v_mfma_f32_16x16x32_f16 v[82:85], v[178:181], v[234:237], v[82:85]
	v_mfma_f32_16x16x32_f16 v[78:81], v[186:189], v[234:237], v[78:81]
	v_mfma_f32_16x16x32_f16 v[122:125], v[190:193], v[206:209], v[122:125]
	v_mfma_f32_16x16x32_f16 v[118:121], v[198:201], v[206:209], v[118:121]
	v_mfma_f32_16x16x32_f16 v[106:109], v[190:193], v[214:217], v[106:109]
	v_mfma_f32_16x16x32_f16 v[102:105], v[198:201], v[214:217], v[102:105]
	v_mfma_f32_16x16x32_f16 v[90:93], v[190:193], v[222:225], v[90:93]
	v_mfma_f32_16x16x32_f16 v[86:89], v[198:201], v[222:225], v[86:89]
	v_mfma_f32_16x16x32_f16 v[74:77], v[190:193], v[230:233], v[74:77]
	v_mfma_f32_16x16x32_f16 v[70:73], v[198:201], v[230:233], v[70:73]
	v_mfma_f32_16x16x32_f16 v[122:125], v[194:197], v[210:213], v[122:125]
	v_mfma_f32_16x16x32_f16 v[118:121], v[202:205], v[210:213], v[118:121]
	v_mfma_f32_16x16x32_f16 v[106:109], v[194:197], v[218:221], v[106:109]
	v_mfma_f32_16x16x32_f16 v[102:105], v[202:205], v[218:221], v[102:105]
	v_mfma_f32_16x16x32_f16 v[90:93], v[194:197], v[226:229], v[90:93]
	v_mfma_f32_16x16x32_f16 v[86:89], v[202:205], v[226:229], v[86:89]
	v_mfma_f32_16x16x32_f16 v[74:77], v[194:197], v[234:237], v[74:77]
	v_mfma_f32_16x16x32_f16 v[70:73], v[202:205], v[234:237], v[70:73]
	s_barrier
; #define STAGE(bufoff, gbase, voff) do { _Pragma("unroll") for (int _i = 0; _i < 2; ++_i) \
;     __builtin_amdgcn_global_load_lds((const unsigned*)((const char*)(gbase) + (voff)[_i]), (LAS unsigned*)(lds + (bufoff) + ldsw + _i * 8192), 16, 0, 0); } while (0)
; #define LDA(dst, b, h) do { _Pragma("unroll") for (int m = 0; m < 4; ++m) _Pragma("unroll") for (int k = 0; k < 2; ++k) dst[m][k] = *(const LAS half8*)(lds + SA(b, h) + aoff + m * 2048 + k * 1024); } while (0)
; #define LDB(dst, b, h) do { _Pragma("unroll") for (int n = 0; n < 2; ++n) _Pragma("unroll") for (int k = 0; k < 2; ++k) dst[n][k] = *(const LAS half8*)(lds + SB(b, h) + boff + n * 2048 + k * 1024); } while (0)
; #define MMA(ai, bj, At_, Bt_) do { __builtin_amdgcn_s_setprio(1); \
;     _Pragma("unroll") for (int m = 0; m < 4; ++m) _Pragma("unroll") for (int n = 0; n < 2; ++n) _Pragma("unroll") for (int k = 0; k < 2; ++k) \
;       acc[ai][bj][m][n] = MFMA16(Bt_[n][k], At_[m][k], acc[ai][bj][m][n]); \
;     __builtin_amdgcn_s_setprio(0); } while (0)
; #define WAIT_V(n) asm volatile("s_waitcnt vmcnt(" #n ")" ::: "memory")
; #define BAR __builtin_amdgcn_s_barrier()
; template <int EPI>
; DI void gemm_phase(const int wid_s, const h16* __restrict__ A, const h16* __restrict__ Bt, const int N, const int K, const EpiArgs ea) {
;     ...
;     for (int t = 0; t < nt; t += 2) {
;       const bool last = (t == nt - 2);
;       const char* a1 = cA + (size_t)(t + 1) * kstep;
;       const char* a2 = last ? nA : cA + (size_t)(t + 2) * kstep; const char* b2 = last ? nB : cB + (size_t)(t + 2) * kstep;
;       const char* a3 = a2 + kstep; const char* b3 = b2 + kstep;
;       LDB(B0, 0, 0); LDB(B1, 0, 1); SCHED; LDA(At, 0, 0); STAGE(SA(1, 1), a1 + hstep, voffA);
;       WAIT_V(8); WAIT_L(0); BAR; MMA(0, 0, At, B0); MMA(0, 1, At, B1); BAR; SCHED;
;       LDA(At, 0, 1); STAGE(SB(0, 0), b2, voffB); STAGE(SB(0, 1), b2 + hstep, voffB); STAGE(SA(0, 0), a2, voffA);
;       WAIT_V(8); WAIT_L(0); BAR; MMA(1, 0, At, B0); MMA(1, 1, At, B1); BAR; SCHED;
;       LDB(B0, 1, 0); LDB(B1, 1, 1); SCHED; LDA(At, 1, 0); STAGE(SA(0, 1), a2 + hstep, voffA);
;       WAIT_V(8); WAIT_L(0); BAR; MMA(0, 0, At, B0); MMA(0, 1, At, B1); BAR; SCHED;
;       LDA(At, 1, 1); STAGE(SB(1, 0), b3, voffB); STAGE(SB(1, 1), b3 + hstep, voffB); STAGE(SA(1, 0), a3, voffA);
;       WAIT_V(8); WAIT_L(0); BAR; MMA(1, 0, At, B0); MMA(1, 1, At, B1); BAR; SCHED;
	s_add_i32 s26, s49, s30
	v_lshl_add_u64 v[238:239], v[238:239], 0, s[36:37]
	s_mov_b32 m0, s26
	ds_read_b128 v[206:209], v151 offset:49152
	ds_read_b128 v[210:213], v151 offset:50176
	ds_read_b128 v[214:217], v151 offset:51200
	ds_read_b128 v[218:221], v151 offset:52224
	ds_read_b128 v[222:225], v151 offset:53248
	ds_read_b128 v[226:229], v151 offset:54272
	ds_read_b128 v[230:233], v151 offset:55296
	ds_read_b128 v[234:237], v151 offset:56320
	global_load_lds_dwordx4 v[238:239], off
	s_add_i32 m0, s26, 0x2000
	s_add_u32 s22, s22, 0x40080
	v_lshl_add_u64 v[238:239], v[240:241], 0, s[36:37]
	s_addc_u32 s23, s23, 0
	s_add_i32 s26, s50, s30
	global_load_lds_dwordx4 v[238:239], off
	v_lshl_add_u64 v[238:239], s[22:23], 0, v[0:1]
	s_mov_b32 m0, s26
	s_nop 0
	global_load_lds_dwordx4 v[238:239], off
	v_lshl_add_u64 v[238:239], s[22:23], 0, v[2:3]
	s_add_i32 m0, s26, 0x2000
	s_nop 0
	global_load_lds_dwordx4 v[238:239], off
	v_lshl_add_u64 v[238:239], v[242:243], 0, s[36:37]
	s_mov_b32 m0, s40
	s_nop 0
	global_load_lds_dwordx4 v[238:239], off
	v_lshl_add_u64 v[238:239], v[244:245], 0, s[36:37]
	s_mov_b32 m0, s41
	s_nop 0
	global_load_lds_dwordx4 v[238:239], off
	s_waitcnt vmcnt(8)
	s_waitcnt lgkmcnt(0)
	s_barrier
	s_waitcnt lgkmcnt(0)
	v_mfma_f32_16x16x32_f16 v[66:69], v[152:155], v[206:209], v[66:69]
	v_mfma_f32_16x16x32_f16 v[62:65], v[182:185], v[206:209], v[62:65]
	v_mfma_f32_16x16x32_f16 v[50:53], v[152:155], v[214:217], v[50:53]
	v_mfma_f32_16x16x32_f16 v[46:49], v[182:185], v[214:217], v[46:49]
	v_mfma_f32_16x16x32_f16 v[34:37], v[152:155], v[222:225], v[34:37]
	v_mfma_f32_16x16x32_f16 v[30:33], v[182:185], v[222:225], v[30:33]
	v_mfma_f32_16x16x32_f16 v[18:21], v[152:155], v[230:233], v[18:21]
	v_mfma_f32_16x16x32_f16 v[14:17], v[182:185], v[230:233], v[14:17]
	v_mfma_f32_16x16x32_f16 v[66:69], v[178:181], v[210:213], v[66:69]
	v_mfma_f32_16x16x32_f16 v[62:65], v[186:189], v[210:213], v[62:65]
	v_mfma_f32_16x16x32_f16 v[50:53], v[178:181], v[218:221], v[50:53]
	v_mfma_f32_16x16x32_f16 v[46:49], v[186:189], v[218:221], v[46:49]
	v_mfma_f32_16x16x32_f16 v[34:37], v[178:181], v[226:229], v[34:37]
	v_mfma_f32_16x16x32_f16 v[30:33], v[186:189], v[226:229], v[30:33]
	v_mfma_f32_16x16x32_f16 v[18:21], v[178:181], v[234:237], v[18:21]
	v_mfma_f32_16x16x32_f16 v[14:17], v[186:189], v[234:237], v[14:17]
	v_mfma_f32_16x16x32_f16 v[58:61], v[190:193], v[206:209], v[58:61]
	v_mfma_f32_16x16x32_f16 v[54:57], v[198:201], v[206:209], v[54:57]
	v_mfma_f32_16x16x32_f16 v[42:45], v[190:193], v[214:217], v[42:45]
	v_mfma_f32_16x16x32_f16 v[38:41], v[198:201], v[214:217], v[38:41]
	v_mfma_f32_16x16x32_f16 v[26:29], v[190:193], v[222:225], v[26:29]
	v_mfma_f32_16x16x32_f16 v[22:25], v[198:201], v[222:225], v[22:25]
	v_mfma_f32_16x16x32_f16 v[10:13], v[190:193], v[230:233], v[10:13]
	v_mfma_f32_16x16x32_f16 v[6:9], v[198:201], v[230:233], v[6:9]
	v_mfma_f32_16x16x32_f16 v[58:61], v[194:197], v[210:213], v[58:61]
	v_mfma_f32_16x16x32_f16 v[54:57], v[202:205], v[210:213], v[54:57]
	v_mfma_f32_16x16x32_f16 v[42:45], v[194:197], v[218:221], v[42:45]
	v_mfma_f32_16x16x32_f16 v[38:41], v[202:205], v[218:221], v[38:41]
	v_mfma_f32_16x16x32_f16 v[26:29], v[194:197], v[226:229], v[26:29]
	v_mfma_f32_16x16x32_f16 v[22:25], v[202:205], v[226:229], v[22:25]
	v_mfma_f32_16x16x32_f16 v[10:13], v[194:197], v[234:237], v[10:13]
	v_mfma_f32_16x16x32_f16 v[6:9], v[202:205], v[234:237], v[6:9]
	s_barrier
	s_add_i32 s48, s48, 2
	s_add_u32 s20, s20, 0x100
	s_addc_u32 s21, s21, 0
	s_cmp_gt_u32 s48, 13

; #define STAGE(bufoff, gbase, voff) do { _Pragma("unroll") for (int _i = 0; _i < 2; ++_i) \
;     __builtin_amdgcn_global_load_lds((const unsigned*)((const char*)(gbase) + (voff)[_i]), (LAS unsigned*)(lds + (bufoff) + ldsw + _i * 8192), 16, 0, 0); } while (0)
; #define LDA(dst, b, h) do { _Pragma("unroll") for (int m = 0; m < 4; ++m) _Pragma("unroll") for (int k = 0; k < 2; ++k) dst[m][k] = *(const LAS half8*)(lds + SA(b, h) + aoff + m * 2048 + k * 1024); } while (0)
; #define LDB(dst, b, h) do { _Pragma("unroll") for (int n = 0; n < 2; ++n) _Pragma("unroll") for (int k = 0; k < 2; ++k) dst[n][k] = *(const LAS half8*)(lds + SB(b, h) + boff + n * 2048 + k * 1024); } while (0)
; #define MMA(ai, bj, At_, Bt_) do { __builtin_amdgcn_s_setprio(1); \
;     _Pragma("unroll") for (int m = 0; m < 4; ++m) _Pragma("unroll") for (int n = 0; n < 2; ++n) _Pragma("unroll") for (int k = 0; k < 2; ++k) \
;       acc[ai][bj][m][n] = MFMA16(Bt_[n][k], At_[m][k], acc[ai][bj][m][n]); \
;     __builtin_amdgcn_s_setprio(0); } while (0)
; #define WAIT_V(n) asm volatile("s_waitcnt vmcnt(" #n ")" ::: "memory")
; #define WAIT_L(n) asm volatile("s_waitcnt lgkmcnt(" #n ")" ::: "memory")
; #define BAR __builtin_amdgcn_s_barrier()
; #define SCHED __builtin_amdgcn_sched_barrier(0)
; template <int EPI>
; DI void gemm_phase(const int wid_s, const h16* __restrict__ A, const h16* __restrict__ Bt, const int N, const int K, const EpiArgs ea) {
;     ...
;     int nbrow = brow, nbcol = bcol;
;     if (has_next) TILE_RC(Ln, nbrow, nbcol);
;     const char* nA = (const char*)A + (size_t)nbrow * K * 2;
;     const char* nB = (const char*)Bt + (size_t)nbcol * K * 2;
;     for (int t = 0; t < nt; t += 2) {
;       const bool last = (t == nt - 2);
;       const char* a1 = cA + (size_t)(t + 1) * kstep;
;       const char* a2 = last ? nA : cA + (size_t)(t + 2) * kstep; const char* b2 = last ? nB : cB + (size_t)(t + 2) * kstep;
;       const char* a3 = a2 + kstep; const char* b3 = b2 + kstep;
;       LDB(B0, 0, 0); LDB(B1, 0, 1); SCHED; LDA(At, 0, 0); STAGE(SA(1, 1), a1 + hstep, voffA);
;       WAIT_V(8); WAIT_L(0); BAR; MMA(0, 0, At, B0); MMA(0, 1, At, B1); BAR; SCHED;
;       LDA(At, 0, 1); STAGE(SB(0, 0), b2, voffB); STAGE(SB(0, 1), b2 + hstep, voffB); STAGE(SA(0, 0), a2, voffA);
;       WAIT_V(8); WAIT_L(0); BAR; MMA(1, 0, At, B0); MMA(1, 1, At, B1); BAR; SCHED;
.LBB0_174:
	s_ashr_i32 s9, s8, 31
	s_lshl_b64 s[12:13], s[8:9], 11
	v_readlane_b32 s14, v250, 46
	v_readlane_b32 s15, v250, 47
	s_add_u32 s12, s14, s12
	s_addc_u32 s13, s15, s13
	s_ashr_i32 s11, s10, 31
	s_lshl_b64 s[14:15], s[10:11], 11
	v_readlane_b32 s9, v249, 6
	s_add_u32 s9, s9, s14
	v_readlane_b32 s11, v249, 7
	s_addc_u32 s11, s11, s15
	v_readlane_b32 s26, v249, 27
	s_add_u32 s41, s26, s20
	v_readlane_b32 s20, v249, 28
	s_addc_u32 s42, s20, s21
	s_add_u32 s20, s22, 0x40080
	v_mov_b32_e32 v6, 0
	s_addc_u32 s21, s23, 0
	s_mov_b32 s43, -2
	s_add_u32 s22, s20, 0xfffc0080
	s_addc_u32 s23, s21, -1
	s_add_i32 s44, 0, 0x10000
	s_cmp_eq_u32 s43, 12
	s_cselect_b32 s27, s13, s23
	s_cselect_b32 s26, s12, s22
	v_add_u32_e32 v177, s44, v148
	s_cselect_b32 s23, s11, s42
	s_cselect_b32 s22, s9, s41
	s_add_i32 s46, 0, 0x14000
	ds_read_b128 v[144:147], v177
	ds_read_b128 v[152:155], v177 offset:1024
	ds_read_b128 v[178:181], v177 offset:2048
	ds_read_b128 v[182:185], v177 offset:3072
	v_add_u32_e32 v177, s46, v148
	ds_read_b128 v[186:189], v177
	ds_read_b128 v[190:193], v177 offset:1024
	ds_read_b128 v[194:197], v177 offset:2048
	ds_read_b128 v[198:201], v177 offset:3072
	v_lshl_add_u64 v[234:235], s[20:21], 0, v[142:143]
	s_add_i32 m0, s17, 0xc000
	ds_read_b128 v[202:205], v151
	ds_read_b128 v[206:209], v151 offset:1024
	ds_read_b128 v[210:213], v151 offset:2048
	ds_read_b128 v[214:217], v151 offset:3072
	ds_read_b128 v[218:221], v151 offset:4096
	ds_read_b128 v[222:225], v151 offset:5120
	ds_read_b128 v[226:229], v151 offset:6144
	ds_read_b128 v[230:233], v151 offset:7168
	global_load_lds_dwordx4 v[234:235], off
	v_lshl_add_u64 v[234:235], s[20:21], 0, v[140:141]
	s_add_i32 m0, s17, 0xe000
	s_nop 0
	global_load_lds_dwordx4 v[234:235], off
	s_waitcnt vmcnt(8)
	s_waitcnt lgkmcnt(0)
	s_barrier
	s_waitcnt lgkmcnt(0)
	v_mfma_f32_16x16x32_f16 v[130:133], v[144:147], v[202:205], 0
	v_mfma_f32_16x16x32_f16 v[126:129], v[178:181], v[202:205], 0
	v_mfma_f32_16x16x32_f16 v[114:117], v[144:147], v[210:213], 0
	v_mfma_f32_16x16x32_f16 v[110:113], v[178:181], v[210:213], 0
	v_mfma_f32_16x16x32_f16 v[98:101], v[144:147], v[218:221], 0
	v_mfma_f32_16x16x32_f16 v[94:97], v[178:181], v[218:221], 0
	v_mfma_f32_16x16x32_f16 v[82:85], v[144:147], v[226:229], 0
	v_mfma_f32_16x16x32_f16 v[78:81], v[178:181], v[226:229], 0
	v_mfma_f32_16x16x32_f16 v[130:133], v[152:155], v[206:209], v[130:133]
	v_mfma_f32_16x16x32_f16 v[126:129], v[182:185], v[206:209], v[126:129]
	v_mfma_f32_16x16x32_f16 v[114:117], v[152:155], v[214:217], v[114:117]
	v_mfma_f32_16x16x32_f16 v[110:113], v[182:185], v[214:217], v[110:113]
	v_mfma_f32_16x16x32_f16 v[98:101], v[152:155], v[222:225], v[98:101]
	v_mfma_f32_16x16x32_f16 v[94:97], v[182:185], v[222:225], v[94:97]
	v_mfma_f32_16x16x32_f16 v[82:85], v[152:155], v[230:233], v[82:85]
	v_mfma_f32_16x16x32_f16 v[78:81], v[182:185], v[230:233], v[78:81]
	v_mfma_f32_16x16x32_f16 v[122:125], v[186:189], v[202:205], 0
	v_mfma_f32_16x16x32_f16 v[118:121], v[194:197], v[202:205], 0
	v_mfma_f32_16x16x32_f16 v[106:109], v[186:189], v[210:213], 0
	v_mfma_f32_16x16x32_f16 v[102:105], v[194:197], v[210:213], 0
	v_mfma_f32_16x16x32_f16 v[90:93], v[186:189], v[218:221], 0
	v_mfma_f32_16x16x32_f16 v[86:89], v[194:197], v[218:221], 0
	v_mfma_f32_16x16x32_f16 v[74:77], v[186:189], v[226:229], 0
	v_mfma_f32_16x16x32_f16 v[70:73], v[194:197], v[226:229], 0
	v_mfma_f32_16x16x32_f16 v[122:125], v[190:193], v[206:209], v[122:125]
	v_mfma_f32_16x16x32_f16 v[118:121], v[198:201], v[206:209], v[118:121]
	v_mfma_f32_16x16x32_f16 v[106:109], v[190:193], v[214:217], v[106:109]
	v_mfma_f32_16x16x32_f16 v[102:105], v[198:201], v[214:217], v[102:105]
	v_mfma_f32_16x16x32_f16 v[90:93], v[190:193], v[222:225], v[90:93]
	v_mfma_f32_16x16x32_f16 v[86:89], v[198:201], v[222:225], v[86:89]
	v_mfma_f32_16x16x32_f16 v[74:77], v[190:193], v[230:233], v[74:77]
	v_mfma_f32_16x16x32_f16 v[70:73], v[198:201], v[230:233], v[70:73]
	s_barrier
	s_add_i32 s44, s44, s30
	v_lshl_add_u64 v[234:235], s[22:23], 0, v[0:1]
	s_mov_b32 m0, s44
	ds_read_b128 v[202:205], v151 offset:16384
	ds_read_b128 v[206:209], v151 offset:17408
	ds_read_b128 v[210:213], v151 offset:18432
	ds_read_b128 v[214:217], v151 offset:19456
	ds_read_b128 v[218:221], v151 offset:20480
	ds_read_b128 v[222:225], v151 offset:21504
	ds_read_b128 v[226:229], v151 offset:22528
	ds_read_b128 v[230:233], v151 offset:23552
	global_load_lds_dwordx4 v[234:235], off
	s_add_i32 m0, s44, 0x2000
	s_add_u32 s44, s22, 0x40000
	v_lshl_add_u64 v[236:237], s[22:23], 0, v[138:139]
	s_addc_u32 s45, s23, 0
	s_add_i32 s46, s46, s30
	global_load_lds_dwordx4 v[236:237], off
	v_lshl_add_u64 v[238:239], s[44:45], 0, v[0:1]
	s_mov_b32 m0, s46
	v_lshl_add_u64 v[240:241], s[26:27], 0, v[134:135]
	global_load_lds_dwordx4 v[238:239], off
	v_lshl_add_u64 v[238:239], s[44:45], 0, v[138:139]
	s_add_i32 m0, s46, 0x2000
	s_nop 0
	global_load_lds_dwordx4 v[238:239], off
	v_lshl_add_u64 v[238:239], s[26:27], 0, v[2:3]
	s_mov_b32 m0, s17
	s_nop 0
	global_load_lds_dwordx4 v[238:239], off
	s_mov_b32 m0, s19
	s_nop 0
	global_load_lds_dwordx4 v[240:241], off
	s_waitcnt vmcnt(8)
	s_waitcnt lgkmcnt(0)
	s_barrier
; #define STAGE(bufoff, gbase, voff) do { _Pragma("unroll") for (int _i = 0; _i < 2; ++_i) \
;     __builtin_amdgcn_global_load_lds((const unsigned*)((const char*)(gbase) + (voff)[_i]), (LAS unsigned*)(lds + (bufoff) + ldsw + _i * 8192), 16, 0, 0); } while (0)
; #define LDA(dst, b, h) do { _Pragma("unroll") for (int m = 0; m < 4; ++m) _Pragma("unroll") for (int k = 0; k < 2; ++k) dst[m][k] = *(const LAS half8*)(lds + SA(b, h) + aoff + m * 2048 + k * 1024); } while (0)
; #define LDB(dst, b, h) do { _Pragma("unroll") for (int n = 0; n < 2; ++n) _Pragma("unroll") for (int k = 0; k < 2; ++k) dst[n][k] = *(const LAS half8*)(lds + SB(b, h) + boff + n * 2048 + k * 1024); } while (0)
; #define MMA(ai, bj, At_, Bt_) do { __builtin_amdgcn_s_setprio(1); \
;     _Pragma("unroll") for (int m = 0; m < 4; ++m) _Pragma("unroll") for (int n = 0; n < 2; ++n) _Pragma("unroll") for (int k = 0; k < 2; ++k) \
;       acc[ai][bj][m][n] = MFMA16(Bt_[n][k], At_[m][k], acc[ai][bj][m][n]); \
;     __builtin_amdgcn_s_setprio(0); } while (0)
; #define WAIT_V(n) asm volatile("s_waitcnt vmcnt(" #n ")" ::: "memory")
; #define WAIT_L(n) asm volatile("s_waitcnt lgkmcnt(" #n ")" ::: "memory")
; #define BAR __builtin_amdgcn_s_barrier()
; #define SCHED __builtin_amdgcn_sched_barrier(0)
; template <int EPI>
; DI void gemm_phase(const int wid_s, const h16* __restrict__ A, const h16* __restrict__ Bt, const int N, const int K, const EpiArgs ea) {
;     ...
;       LDB(B0, 0, 0); LDB(B1, 0, 1); SCHED; LDA(At, 0, 0); STAGE(SA(1, 1), a1 + hstep, voffA);
;       WAIT_V(8); WAIT_L(0); BAR; MMA(0, 0, At, B0); MMA(0, 1, At, B1); BAR; SCHED;
;       LDA(At, 0, 1); STAGE(SB(0, 0), b2, voffB); STAGE(SB(0, 1), b2 + hstep, voffB); STAGE(SA(0, 0), a2, voffA);
;       WAIT_V(8); WAIT_L(0); BAR; MMA(1, 0, At, B0); MMA(1, 1, At, B1); BAR; SCHED;
;       LDB(B0, 1, 0); LDB(B1, 1, 1); SCHED; LDA(At, 1, 0); STAGE(SA(0, 1), a2 + hstep, voffA);
;       WAIT_V(8); WAIT_L(0); BAR; MMA(0, 0, At, B0); MMA(0, 1, At, B1); BAR; SCHED;
	s_waitcnt lgkmcnt(0)
	v_mfma_f32_16x16x32_f16 v[66:69], v[144:147], v[202:205], 0
	v_mfma_f32_16x16x32_f16 v[62:65], v[178:181], v[202:205], 0
	v_mfma_f32_16x16x32_f16 v[50:53], v[144:147], v[210:213], 0
	v_mfma_f32_16x16x32_f16 v[46:49], v[178:181], v[210:213], 0
	v_mfma_f32_16x16x32_f16 v[34:37], v[144:147], v[218:221], 0
	v_mfma_f32_16x16x32_f16 v[30:33], v[178:181], v[218:221], 0
	v_mfma_f32_16x16x32_f16 v[18:21], v[144:147], v[226:229], 0
	v_mfma_f32_16x16x32_f16 v[14:17], v[178:181], v[226:229], 0
	v_mfma_f32_16x16x32_f16 v[66:69], v[152:155], v[206:209], v[66:69]
	v_mfma_f32_16x16x32_f16 v[62:65], v[182:185], v[206:209], v[62:65]
	v_mfma_f32_16x16x32_f16 v[50:53], v[152:155], v[214:217], v[50:53]
	v_mfma_f32_16x16x32_f16 v[46:49], v[182:185], v[214:217], v[46:49]
	v_mfma_f32_16x16x32_f16 v[34:37], v[152:155], v[222:225], v[34:37]
	v_mfma_f32_16x16x32_f16 v[30:33], v[182:185], v[222:225], v[30:33]
	v_mfma_f32_16x16x32_f16 v[18:21], v[152:155], v[230:233], v[18:21]
	v_mfma_f32_16x16x32_f16 v[14:17], v[182:185], v[230:233], v[14:17]
	v_mfma_f32_16x16x32_f16 v[58:61], v[186:189], v[202:205], 0
	v_mfma_f32_16x16x32_f16 v[54:57], v[194:197], v[202:205], 0
	v_mfma_f32_16x16x32_f16 v[42:45], v[186:189], v[210:213], 0
	v_mfma_f32_16x16x32_f16 v[38:41], v[194:197], v[210:213], 0
	v_mfma_f32_16x16x32_f16 v[26:29], v[186:189], v[218:221], 0
	v_mfma_f32_16x16x32_f16 v[22:25], v[194:197], v[218:221], 0
	v_mfma_f32_16x16x32_f16 v[10:13], v[186:189], v[226:229], 0
	v_mfma_f32_16x16x32_f16 v[6:9], v[194:197], v[226:229], 0
	v_mfma_f32_16x16x32_f16 v[58:61], v[190:193], v[206:209], v[58:61]
	v_mfma_f32_16x16x32_f16 v[54:57], v[198:201], v[206:209], v[54:57]
	v_mfma_f32_16x16x32_f16 v[42:45], v[190:193], v[214:217], v[42:45]
	v_mfma_f32_16x16x32_f16 v[38:41], v[198:201], v[214:217], v[38:41]
	v_mfma_f32_16x16x32_f16 v[26:29], v[190:193], v[222:225], v[26:29]
	v_mfma_f32_16x16x32_f16 v[22:25], v[198:201], v[222:225], v[22:25]
	v_mfma_f32_16x16x32_f16 v[10:13], v[190:193], v[230:233], v[10:13]
	v_mfma_f32_16x16x32_f16 v[6:9], v[198:201], v[230:233], v[6:9]
	s_barrier
	s_add_i32 s44, 0, 0x18000
	v_add_u32_e32 v177, s44, v148
	s_add_i32 s45, 0, 0x1c000
	ds_read_b128 v[144:147], v177
	ds_read_b128 v[152:155], v177 offset:1024
	ds_read_b128 v[178:181], v177 offset:2048
	ds_read_b128 v[182:185], v177 offset:3072
	v_add_u32_e32 v177, s45, v148
	ds_read_b128 v[186:189], v177
	ds_read_b128 v[190:193], v177 offset:1024
	ds_read_b128 v[194:197], v177 offset:2048
	ds_read_b128 v[198:201], v177 offset:3072
	s_add_u32 s26, s26, 0x40000
	s_addc_u32 s27, s27, 0
	s_mov_b32 m0, s31
	v_lshl_add_u64 v[242:243], s[26:27], 0, v[2:3]
	ds_read_b128 v[202:205], v151 offset:32768
	ds_read_b128 v[206:209], v151 offset:33792
	ds_read_b128 v[210:213], v151 offset:34816
	ds_read_b128 v[214:217], v151 offset:35840
	ds_read_b128 v[218:221], v151 offset:36864
	ds_read_b128 v[222:225], v151 offset:37888
	ds_read_b128 v[226:229], v151 offset:38912
	ds_read_b128 v[230:233], v151 offset:39936
	global_load_lds_dwordx4 v[242:243], off
	v_lshl_add_u64 v[242:243], s[26:27], 0, v[134:135]
	s_mov_b32 m0, s38
	s_nop 0
	global_load_lds_dwordx4 v[242:243], off
	s_waitcnt vmcnt(8)
	s_waitcnt lgkmcnt(0)
	s_barrier
	s_waitcnt lgkmcnt(0)
	v_mfma_f32_16x16x32_f16 v[130:133], v[144:147], v[202:205], v[130:133]
	v_mfma_f32_16x16x32_f16 v[126:129], v[178:181], v[202:205], v[126:129]
	v_mfma_f32_16x16x32_f16 v[114:117], v[144:147], v[210:213], v[114:117]
	v_mfma_f32_16x16x32_f16 v[110:113], v[178:181], v[210:213], v[110:113]
	v_mfma_f32_16x16x32_f16 v[98:101], v[144:147], v[218:221], v[98:101]
	v_mfma_f32_16x16x32_f16 v[94:97], v[178:181], v[218:221], v[94:97]
	v_mfma_f32_16x16x32_f16 v[82:85], v[144:147], v[226:229], v[82:85]
	v_mfma_f32_16x16x32_f16 v[78:81], v[178:181], v[226:229], v[78:81]
	v_mfma_f32_16x16x32_f16 v[130:133], v[152:155], v[206:209], v[130:133]
	v_mfma_f32_16x16x32_f16 v[126:129], v[182:185], v[206:209], v[126:129]
	v_mfma_f32_16x16x32_f16 v[114:117], v[152:155], v[214:217], v[114:117]
	v_mfma_f32_16x16x32_f16 v[110:113], v[182:185], v[214:217], v[110:113]
	v_mfma_f32_16x16x32_f16 v[98:101], v[152:155], v[222:225], v[98:101]
	v_mfma_f32_16x16x32_f16 v[94:97], v[182:185], v[222:225], v[94:97]
	v_mfma_f32_16x16x32_f16 v[82:85], v[152:155], v[230:233], v[82:85]
	v_mfma_f32_16x16x32_f16 v[78:81], v[182:185], v[230:233], v[78:81]
	v_mfma_f32_16x16x32_f16 v[122:125], v[186:189], v[202:205], v[122:125]
	v_mfma_f32_16x16x32_f16 v[118:121], v[194:197], v[202:205], v[118:121]
	v_mfma_f32_16x16x32_f16 v[106:109], v[186:189], v[210:213], v[106:109]
	v_mfma_f32_16x16x32_f16 v[102:105], v[194:197], v[210:213], v[102:105]
	v_mfma_f32_16x16x32_f16 v[90:93], v[186:189], v[218:221], v[90:93]
	v_mfma_f32_16x16x32_f16 v[86:89], v[194:197], v[218:221], v[86:89]
	v_mfma_f32_16x16x32_f16 v[74:77], v[186:189], v[226:229], v[74:77]
	v_mfma_f32_16x16x32_f16 v[70:73], v[194:197], v[226:229], v[70:73]
	v_mfma_f32_16x16x32_f16 v[122:125], v[190:193], v[206:209], v[122:125]
	v_mfma_f32_16x16x32_f16 v[118:121], v[198:201], v[206:209], v[118:121]
	v_mfma_f32_16x16x32_f16 v[106:109], v[190:193], v[214:217], v[106:109]
	v_mfma_f32_16x16x32_f16 v[102:105], v[198:201], v[214:217], v[102:105]
	v_mfma_f32_16x16x32_f16 v[90:93], v[190:193], v[222:225], v[90:93]
	v_mfma_f32_16x16x32_f16 v[86:89], v[198:201], v[222:225], v[86:89]
	v_mfma_f32_16x16x32_f16 v[74:77], v[190:193], v[230:233], v[74:77]
	v_mfma_f32_16x16x32_f16 v[70:73], v[198:201], v[230:233], v[70:73]
	s_barrier
; #define STAGE(bufoff, gbase, voff) do { _Pragma("unroll") for (int _i = 0; _i < 2; ++_i) \
;     __builtin_amdgcn_global_load_lds((const unsigned*)((const char*)(gbase) + (voff)[_i]), (LAS unsigned*)(lds + (bufoff) + ldsw + _i * 8192), 16, 0, 0); } while (0)
; #define LDA(dst, b, h) do { _Pragma("unroll") for (int m = 0; m < 4; ++m) _Pragma("unroll") for (int k = 0; k < 2; ++k) dst[m][k] = *(const LAS half8*)(lds + SA(b, h) + aoff + m * 2048 + k * 1024); } while (0)
; #define LDB(dst, b, h) do { _Pragma("unroll") for (int n = 0; n < 2; ++n) _Pragma("unroll") for (int k = 0; k < 2; ++k) dst[n][k] = *(const LAS half8*)(lds + SB(b, h) + boff + n * 2048 + k * 1024); } while (0)
; #define MMA(ai, bj, At_, Bt_) do { __builtin_amdgcn_s_setprio(1); \
;     _Pragma("unroll") for (int m = 0; m < 4; ++m) _Pragma("unroll") for (int n = 0; n < 2; ++n) _Pragma("unroll") for (int k = 0; k < 2; ++k) \
;       acc[ai][bj][m][n] = MFMA16(Bt_[n][k], At_[m][k], acc[ai][bj][m][n]); \
;     __builtin_amdgcn_s_setprio(0); } while (0)
; #define WAIT_V(n) asm volatile("s_waitcnt vmcnt(" #n ")" ::: "memory")
; #define BAR __builtin_amdgcn_s_barrier()
; template <int EPI>
; DI void gemm_phase(const int wid_s, const h16* __restrict__ A, const h16* __restrict__ Bt, const int N, const int K, const EpiArgs ea) {
;     ...
;     for (int t = 0; t < nt; t += 2) {
;       const bool last = (t == nt - 2);
;       const char* a1 = cA + (size_t)(t + 1) * kstep;
;       const char* a2 = last ? nA : cA + (size_t)(t + 2) * kstep; const char* b2 = last ? nB : cB + (size_t)(t + 2) * kstep;
;       const char* a3 = a2 + kstep; const char* b3 = b2 + kstep;
;       LDB(B0, 0, 0); LDB(B1, 0, 1); SCHED; LDA(At, 0, 0); STAGE(SA(1, 1), a1 + hstep, voffA);
;       WAIT_V(8); WAIT_L(0); BAR; MMA(0, 0, At, B0); MMA(0, 1, At, B1); BAR; SCHED;
;       LDA(At, 0, 1); STAGE(SB(0, 0), b2, voffB); STAGE(SB(0, 1), b2 + hstep, voffB); STAGE(SA(0, 0), a2, voffA);
;       WAIT_V(8); WAIT_L(0); BAR; MMA(1, 0, At, B0); MMA(1, 1, At, B1); BAR; SCHED;
;       LDB(B0, 1, 0); LDB(B1, 1, 1); SCHED; LDA(At, 1, 0); STAGE(SA(0, 1), a2 + hstep, voffA);
;       WAIT_V(8); WAIT_L(0); BAR; MMA(0, 0, At, B0); MMA(0, 1, At, B1); BAR; SCHED;
;       LDA(At, 1, 1); STAGE(SB(1, 0), b3, voffB); STAGE(SB(1, 1), b3 + hstep, voffB); STAGE(SA(1, 0), a3, voffA);
;       WAIT_V(8); WAIT_L(0); BAR; MMA(1, 0, At, B0); MMA(1, 1, At, B1); BAR; SCHED;
	s_add_i32 s26, s44, s30
	v_lshl_add_u64 v[234:235], v[234:235], 0, s[36:37]
	s_mov_b32 m0, s26
	ds_read_b128 v[202:205], v151 offset:49152
	ds_read_b128 v[206:209], v151 offset:50176
	ds_read_b128 v[210:213], v151 offset:51200
	ds_read_b128 v[214:217], v151 offset:52224
	ds_read_b128 v[218:221], v151 offset:53248
	ds_read_b128 v[222:225], v151 offset:54272
	ds_read_b128 v[226:229], v151 offset:55296
	ds_read_b128 v[230:233], v151 offset:56320
	global_load_lds_dwordx4 v[234:235], off
	s_add_i32 m0, s26, 0x2000
	s_add_u32 s22, s22, 0x40080
	v_lshl_add_u64 v[234:235], v[236:237], 0, s[36:37]
	s_addc_u32 s23, s23, 0
	s_add_i32 s26, s45, s30
	global_load_lds_dwordx4 v[234:235], off
	v_lshl_add_u64 v[234:235], s[22:23], 0, v[0:1]
	s_mov_b32 m0, s26
	s_nop 0
	global_load_lds_dwordx4 v[234:235], off
	v_lshl_add_u64 v[234:235], s[22:23], 0, v[138:139]
	s_add_i32 m0, s26, 0x2000
	s_nop 0
	global_load_lds_dwordx4 v[234:235], off
	v_lshl_add_u64 v[234:235], v[238:239], 0, s[36:37]
	s_mov_b32 m0, s39
	s_nop 0
	global_load_lds_dwordx4 v[234:235], off
	v_lshl_add_u64 v[234:235], v[240:241], 0, s[36:37]
	s_mov_b32 m0, s40
	s_nop 0
	global_load_lds_dwordx4 v[234:235], off
	s_waitcnt vmcnt(8)
	s_waitcnt lgkmcnt(0)
	s_barrier
	s_waitcnt lgkmcnt(0)
	v_mfma_f32_16x16x32_f16 v[66:69], v[144:147], v[202:205], v[66:69]
	v_mfma_f32_16x16x32_f16 v[62:65], v[178:181], v[202:205], v[62:65]
	v_mfma_f32_16x16x32_f16 v[50:53], v[144:147], v[210:213], v[50:53]
	v_mfma_f32_16x16x32_f16 v[46:49], v[178:181], v[210:213], v[46:49]
	v_mfma_f32_16x16x32_f16 v[34:37], v[144:147], v[218:221], v[34:37]
	v_mfma_f32_16x16x32_f16 v[30:33], v[178:181], v[218:221], v[30:33]
	v_mfma_f32_16x16x32_f16 v[18:21], v[144:147], v[226:229], v[18:21]
	v_mfma_f32_16x16x32_f16 v[14:17], v[178:181], v[226:229], v[14:17]
	v_mfma_f32_16x16x32_f16 v[66:69], v[152:155], v[206:209], v[66:69]
	v_mfma_f32_16x16x32_f16 v[62:65], v[182:185], v[206:209], v[62:65]
	v_mfma_f32_16x16x32_f16 v[50:53], v[152:155], v[214:217], v[50:53]
	v_mfma_f32_16x16x32_f16 v[46:49], v[182:185], v[214:217], v[46:49]
	v_mfma_f32_16x16x32_f16 v[34:37], v[152:155], v[222:225], v[34:37]
	v_mfma_f32_16x16x32_f16 v[30:33], v[182:185], v[222:225], v[30:33]
	v_mfma_f32_16x16x32_f16 v[18:21], v[152:155], v[230:233], v[18:21]
	v_mfma_f32_16x16x32_f16 v[14:17], v[182:185], v[230:233], v[14:17]
	v_mfma_f32_16x16x32_f16 v[58:61], v[186:189], v[202:205], v[58:61]
	v_mfma_f32_16x16x32_f16 v[54:57], v[194:197], v[202:205], v[54:57]
	v_mfma_f32_16x16x32_f16 v[42:45], v[186:189], v[210:213], v[42:45]
	v_mfma_f32_16x16x32_f16 v[38:41], v[194:197], v[210:213], v[38:41]
	v_mfma_f32_16x16x32_f16 v[26:29], v[186:189], v[218:221], v[26:29]
	v_mfma_f32_16x16x32_f16 v[22:25], v[194:197], v[218:221], v[22:25]
	v_mfma_f32_16x16x32_f16 v[10:13], v[186:189], v[226:229], v[10:13]
	v_mfma_f32_16x16x32_f16 v[6:9], v[194:197], v[226:229], v[6:9]
	v_mfma_f32_16x16x32_f16 v[58:61], v[190:193], v[206:209], v[58:61]
	v_mfma_f32_16x16x32_f16 v[54:57], v[198:201], v[206:209], v[54:57]
	v_mfma_f32_16x16x32_f16 v[42:45], v[190:193], v[214:217], v[42:45]
	v_mfma_f32_16x16x32_f16 v[38:41], v[198:201], v[214:217], v[38:41]
	v_mfma_f32_16x16x32_f16 v[26:29], v[190:193], v[222:225], v[26:29]
	v_mfma_f32_16x16x32_f16 v[22:25], v[198:201], v[222:225], v[22:25]
	v_mfma_f32_16x16x32_f16 v[10:13], v[190:193], v[230:233], v[10:13]
	v_mfma_f32_16x16x32_f16 v[6:9], v[198:201], v[230:233], v[6:9]
	s_barrier
	s_add_i32 s43, s43, 2
	s_add_u32 s41, s41, 0x100
	s_addc_u32 s42, s42, 0
	s_add_u32 s20, s20, 0x100
	s_addc_u32 s21, s21, 0
	s_cmp_gt_u32 s43, 13

; #define STAGE(bufoff, gbase, voff) do { _Pragma("unroll") for (int _i = 0; _i < 2; ++_i) \
;     __builtin_amdgcn_global_load_lds((const unsigned*)((const char*)(gbase) + (voff)[_i]), (LAS unsigned*)(lds + (bufoff) + ldsw + _i * 8192), 16, 0, 0); } while (0)
; #define LDA(dst, b, h) do { _Pragma("unroll") for (int m = 0; m < 4; ++m) _Pragma("unroll") for (int k = 0; k < 2; ++k) dst[m][k] = *(const LAS half8*)(lds + SA(b, h) + aoff + m * 2048 + k * 1024); } while (0)
; #define LDB(dst, b, h) do { _Pragma("unroll") for (int n = 0; n < 2; ++n) _Pragma("unroll") for (int k = 0; k < 2; ++k) dst[n][k] = *(const LAS half8*)(lds + SB(b, h) + boff + n * 2048 + k * 1024); } while (0)
; #define MMA(ai, bj, At_, Bt_) do { __builtin_amdgcn_s_setprio(1); \
;     _Pragma("unroll") for (int m = 0; m < 4; ++m) _Pragma("unroll") for (int n = 0; n < 2; ++n) _Pragma("unroll") for (int k = 0; k < 2; ++k) \
;       acc[ai][bj][m][n] = MFMA16(Bt_[n][k], At_[m][k], acc[ai][bj][m][n]); \
;     __builtin_amdgcn_s_setprio(0); } while (0)
; #define WAIT_V(n) asm volatile("s_waitcnt vmcnt(" #n ")" ::: "memory")
; #define WAIT_L(n) asm volatile("s_waitcnt lgkmcnt(" #n ")" ::: "memory")
; #define BAR __builtin_amdgcn_s_barrier()
; #define SCHED __builtin_amdgcn_sched_barrier(0)
; template <int EPI>
; DI void gemm_phase(const int wid_s, const h16* __restrict__ A, const h16* __restrict__ Bt, const int N, const int K, const EpiArgs ea) {
;     ...
;     int nbrow = brow, nbcol = bcol;
;     if (has_next) TILE_RC(Ln, nbrow, nbcol);
;     const char* nA = (const char*)A + (size_t)nbrow * K * 2;
;     const char* nB = (const char*)Bt + (size_t)nbcol * K * 2;
;     for (int t = 0; t < nt; t += 2) {
;       const bool last = (t == nt - 2);
;       const char* a1 = cA + (size_t)(t + 1) * kstep;
;       const char* a2 = last ? nA : cA + (size_t)(t + 2) * kstep; const char* b2 = last ? nB : cB + (size_t)(t + 2) * kstep;
;       const char* a3 = a2 + kstep; const char* b3 = b2 + kstep;
;       LDB(B0, 0, 0); LDB(B1, 0, 1); SCHED; LDA(At, 0, 0); STAGE(SA(1, 1), a1 + hstep, voffA);
;       WAIT_V(8); WAIT_L(0); BAR; MMA(0, 0, At, B0); MMA(0, 1, At, B1); BAR; SCHED;
;       LDA(At, 0, 1); STAGE(SB(0, 0), b2, voffB); STAGE(SB(0, 1), b2 + hstep, voffB); STAGE(SA(0, 0), a2, voffA);
;       WAIT_V(8); WAIT_L(0); BAR; MMA(1, 0, At, B0); MMA(1, 1, At, B1); BAR; SCHED;
.LBB0_385:
	s_ashr_i32 s9, s8, 31
	s_lshl_b64 s[16:17], s[8:9], 11
	s_add_u32 s9, s92, s16
	s_addc_u32 s41, s93, s17
	s_ashr_i32 s11, s10, 31
	s_lshl_b64 s[18:19], s[10:11], 11
	v_readlane_b32 s11, v249, 29
	s_add_u32 s11, s11, s18
	v_readlane_b32 s26, v249, 31
	s_addc_u32 s42, s26, s19
	v_readlane_b32 s26, v249, 30
	s_add_u32 s43, s26, s22
	v_readlane_b32 s22, v249, 32
	s_addc_u32 s44, s22, s23
	s_add_u32 s45, s86, s20
	v_mov_b32_e32 v6, 0
	v_lshl_add_u64 v[144:145], v[140:141], 0, s[20:21]
	v_lshl_add_u64 v[146:147], v[142:143], 0, s[20:21]
	s_addc_u32 s46, s87, s21
	s_mov_b32 s47, -2
	s_mov_b64 s[20:21], 0
	s_add_u32 s22, s45, s20
	s_addc_u32 s23, s46, s21
	s_add_u32 s22, s22, 0x520e100
	s_addc_u32 s23, s23, 0
	s_add_u32 s48, s43, s20
	s_addc_u32 s49, s44, s21
	s_add_i32 s50, 0, 0x10000
	s_cmpk_eq_i32 s20, 0x700
	s_cselect_b32 s27, s41, s23
	s_cselect_b32 s26, s9, s22
	v_add_u32_e32 v177, s50, v148
	s_cselect_b32 s23, s42, s49
	s_cselect_b32 s22, s11, s48
	s_add_i32 s51, 0, 0x14000
	ds_read_b128 v[152:155], v177
	ds_read_b128 v[178:181], v177 offset:1024
	ds_read_b128 v[182:185], v177 offset:2048
	ds_read_b128 v[186:189], v177 offset:3072
	v_add_u32_e32 v177, s51, v148
	ds_read_b128 v[190:193], v177
	ds_read_b128 v[194:197], v177 offset:1024
	ds_read_b128 v[198:201], v177 offset:2048
	ds_read_b128 v[202:205], v177 offset:3072
	v_lshl_add_u64 v[238:239], v[146:147], 0, s[20:21]
	s_add_i32 m0, s13, 0xc000
	ds_read_b128 v[206:209], v151
	ds_read_b128 v[210:213], v151 offset:1024
	ds_read_b128 v[214:217], v151 offset:2048
	ds_read_b128 v[218:221], v151 offset:3072
	ds_read_b128 v[222:225], v151 offset:4096
	ds_read_b128 v[226:229], v151 offset:5120
	ds_read_b128 v[230:233], v151 offset:6144
	ds_read_b128 v[234:237], v151 offset:7168
	global_load_lds_dwordx4 v[238:239], off
	v_lshl_add_u64 v[238:239], v[144:145], 0, s[20:21]
	s_add_i32 m0, s13, 0xe000
	s_nop 0
	global_load_lds_dwordx4 v[238:239], off
	s_waitcnt vmcnt(8)
	s_waitcnt lgkmcnt(0)
	s_barrier
	s_waitcnt lgkmcnt(0)
	v_mfma_f32_16x16x32_f16 v[130:133], v[152:155], v[206:209], 0
	v_mfma_f32_16x16x32_f16 v[126:129], v[182:185], v[206:209], 0
	v_mfma_f32_16x16x32_f16 v[122:125], v[152:155], v[214:217], 0
	v_mfma_f32_16x16x32_f16 v[118:121], v[182:185], v[214:217], 0
	v_mfma_f32_16x16x32_f16 v[106:109], v[152:155], v[222:225], 0
	v_mfma_f32_16x16x32_f16 v[102:105], v[182:185], v[222:225], 0
	v_mfma_f32_16x16x32_f16 v[90:93], v[152:155], v[230:233], 0
	v_mfma_f32_16x16x32_f16 v[86:89], v[182:185], v[230:233], 0
	v_mfma_f32_16x16x32_f16 v[130:133], v[178:181], v[210:213], v[130:133]
	v_mfma_f32_16x16x32_f16 v[126:129], v[186:189], v[210:213], v[126:129]
	v_mfma_f32_16x16x32_f16 v[122:125], v[178:181], v[218:221], v[122:125]
	v_mfma_f32_16x16x32_f16 v[118:121], v[186:189], v[218:221], v[118:121]
	v_mfma_f32_16x16x32_f16 v[106:109], v[178:181], v[226:229], v[106:109]
	v_mfma_f32_16x16x32_f16 v[102:105], v[186:189], v[226:229], v[102:105]
	v_mfma_f32_16x16x32_f16 v[90:93], v[178:181], v[234:237], v[90:93]
	v_mfma_f32_16x16x32_f16 v[86:89], v[186:189], v[234:237], v[86:89]
	v_mfma_f32_16x16x32_f16 v[114:117], v[190:193], v[206:209], 0
	v_mfma_f32_16x16x32_f16 v[110:113], v[198:201], v[206:209], 0
	v_mfma_f32_16x16x32_f16 v[98:101], v[190:193], v[214:217], 0
	v_mfma_f32_16x16x32_f16 v[94:97], v[198:201], v[214:217], 0
	v_mfma_f32_16x16x32_f16 v[82:85], v[190:193], v[222:225], 0
	v_mfma_f32_16x16x32_f16 v[78:81], v[198:201], v[222:225], 0
	v_mfma_f32_16x16x32_f16 v[74:77], v[190:193], v[230:233], 0
	v_mfma_f32_16x16x32_f16 v[70:73], v[198:201], v[230:233], 0
	v_mfma_f32_16x16x32_f16 v[114:117], v[194:197], v[210:213], v[114:117]
	v_mfma_f32_16x16x32_f16 v[110:113], v[202:205], v[210:213], v[110:113]
	v_mfma_f32_16x16x32_f16 v[98:101], v[194:197], v[218:221], v[98:101]
	v_mfma_f32_16x16x32_f16 v[94:97], v[202:205], v[218:221], v[94:97]
	v_mfma_f32_16x16x32_f16 v[82:85], v[194:197], v[226:229], v[82:85]
	v_mfma_f32_16x16x32_f16 v[78:81], v[202:205], v[226:229], v[78:81]
	v_mfma_f32_16x16x32_f16 v[74:77], v[194:197], v[234:237], v[74:77]
	v_mfma_f32_16x16x32_f16 v[70:73], v[202:205], v[234:237], v[70:73]
	s_barrier
	s_add_i32 s48, s50, s30
	v_lshl_add_u64 v[238:239], s[22:23], 0, v[0:1]
	s_mov_b32 m0, s48
	ds_read_b128 v[206:209], v151 offset:16384
	ds_read_b128 v[210:213], v151 offset:17408
	ds_read_b128 v[214:217], v151 offset:18432
	ds_read_b128 v[218:221], v151 offset:19456
	ds_read_b128 v[222:225], v151 offset:20480
	ds_read_b128 v[226:229], v151 offset:21504
	ds_read_b128 v[230:233], v151 offset:22528
	ds_read_b128 v[234:237], v151 offset:23552
	global_load_lds_dwordx4 v[238:239], off
	s_add_i32 m0, s48, 0x2000
	s_add_u32 s48, s22, 0x40000
	v_lshl_add_u64 v[240:241], s[22:23], 0, v[2:3]
	s_addc_u32 s49, s23, 0
	s_add_i32 s50, s51, s30
	global_load_lds_dwordx4 v[240:241], off
	v_lshl_add_u64 v[242:243], s[48:49], 0, v[0:1]
	s_mov_b32 m0, s50
	v_lshl_add_u64 v[244:245], s[26:27], 0, v[134:135]
	global_load_lds_dwordx4 v[242:243], off
	v_lshl_add_u64 v[242:243], s[48:49], 0, v[2:3]
	s_add_i32 m0, s50, 0x2000
	s_nop 0
	global_load_lds_dwordx4 v[242:243], off
	v_lshl_add_u64 v[242:243], s[26:27], 0, v[138:139]
	s_mov_b32 m0, s13
	s_nop 0
	global_load_lds_dwordx4 v[242:243], off
	s_mov_b32 m0, s15
	s_nop 0
	global_load_lds_dwordx4 v[244:245], off
	s_waitcnt vmcnt(8)
	s_waitcnt lgkmcnt(0)
	s_barrier
; #define STAGE(bufoff, gbase, voff) do { _Pragma("unroll") for (int _i = 0; _i < 2; ++_i) \
;     __builtin_amdgcn_global_load_lds((const unsigned*)((const char*)(gbase) + (voff)[_i]), (LAS unsigned*)(lds + (bufoff) + ldsw + _i * 8192), 16, 0, 0); } while (0)
; #define LDA(dst, b, h) do { _Pragma("unroll") for (int m = 0; m < 4; ++m) _Pragma("unroll") for (int k = 0; k < 2; ++k) dst[m][k] = *(const LAS half8*)(lds + SA(b, h) + aoff + m * 2048 + k * 1024); } while (0)
; #define LDB(dst, b, h) do { _Pragma("unroll") for (int n = 0; n < 2; ++n) _Pragma("unroll") for (int k = 0; k < 2; ++k) dst[n][k] = *(const LAS half8*)(lds + SB(b, h) + boff + n * 2048 + k * 1024); } while (0)
; #define MMA(ai, bj, At_, Bt_) do { __builtin_amdgcn_s_setprio(1); \
;     _Pragma("unroll") for (int m = 0; m < 4; ++m) _Pragma("unroll") for (int n = 0; n < 2; ++n) _Pragma("unroll") for (int k = 0; k < 2; ++k) \
;       acc[ai][bj][m][n] = MFMA16(Bt_[n][k], At_[m][k], acc[ai][bj][m][n]); \
;     __builtin_amdgcn_s_setprio(0); } while (0)
; #define WAIT_V(n) asm volatile("s_waitcnt vmcnt(" #n ")" ::: "memory")
; #define WAIT_L(n) asm volatile("s_waitcnt lgkmcnt(" #n ")" ::: "memory")
; #define BAR __builtin_amdgcn_s_barrier()
; #define SCHED __builtin_amdgcn_sched_barrier(0)
; template <int EPI>
; DI void gemm_phase(const int wid_s, const h16* __restrict__ A, const h16* __restrict__ Bt, const int N, const int K, const EpiArgs ea) {
;     ...
;       LDB(B0, 0, 0); LDB(B1, 0, 1); SCHED; LDA(At, 0, 0); STAGE(SA(1, 1), a1 + hstep, voffA);
;       WAIT_V(8); WAIT_L(0); BAR; MMA(0, 0, At, B0); MMA(0, 1, At, B1); BAR; SCHED;
;       LDA(At, 0, 1); STAGE(SB(0, 0), b2, voffB); STAGE(SB(0, 1), b2 + hstep, voffB); STAGE(SA(0, 0), a2, voffA);
;       WAIT_V(8); WAIT_L(0); BAR; MMA(1, 0, At, B0); MMA(1, 1, At, B1); BAR; SCHED;
;       LDB(B0, 1, 0); LDB(B1, 1, 1); SCHED; LDA(At, 1, 0); STAGE(SA(0, 1), a2 + hstep, voffA);
;       WAIT_V(8); WAIT_L(0); BAR; MMA(0, 0, At, B0); MMA(0, 1, At, B1); BAR; SCHED;
	s_waitcnt lgkmcnt(0)
	v_mfma_f32_16x16x32_f16 v[66:69], v[152:155], v[206:209], 0
	v_mfma_f32_16x16x32_f16 v[62:65], v[182:185], v[206:209], 0
	v_mfma_f32_16x16x32_f16 v[58:61], v[152:155], v[214:217], 0
	v_mfma_f32_16x16x32_f16 v[54:57], v[182:185], v[214:217], 0
	v_mfma_f32_16x16x32_f16 v[42:45], v[152:155], v[222:225], 0
	v_mfma_f32_16x16x32_f16 v[38:41], v[182:185], v[222:225], 0
	v_mfma_f32_16x16x32_f16 v[26:29], v[152:155], v[230:233], 0
	v_mfma_f32_16x16x32_f16 v[22:25], v[182:185], v[230:233], 0
	v_mfma_f32_16x16x32_f16 v[66:69], v[178:181], v[210:213], v[66:69]
	v_mfma_f32_16x16x32_f16 v[62:65], v[186:189], v[210:213], v[62:65]
	v_mfma_f32_16x16x32_f16 v[58:61], v[178:181], v[218:221], v[58:61]
	v_mfma_f32_16x16x32_f16 v[54:57], v[186:189], v[218:221], v[54:57]
	v_mfma_f32_16x16x32_f16 v[42:45], v[178:181], v[226:229], v[42:45]
	v_mfma_f32_16x16x32_f16 v[38:41], v[186:189], v[226:229], v[38:41]
	v_mfma_f32_16x16x32_f16 v[26:29], v[178:181], v[234:237], v[26:29]
	v_mfma_f32_16x16x32_f16 v[22:25], v[186:189], v[234:237], v[22:25]
	v_mfma_f32_16x16x32_f16 v[50:53], v[190:193], v[206:209], 0
	v_mfma_f32_16x16x32_f16 v[46:49], v[198:201], v[206:209], 0
	v_mfma_f32_16x16x32_f16 v[34:37], v[190:193], v[214:217], 0
	v_mfma_f32_16x16x32_f16 v[30:33], v[198:201], v[214:217], 0
	v_mfma_f32_16x16x32_f16 v[18:21], v[190:193], v[222:225], 0
	v_mfma_f32_16x16x32_f16 v[14:17], v[198:201], v[222:225], 0
	v_mfma_f32_16x16x32_f16 v[10:13], v[190:193], v[230:233], 0
	v_mfma_f32_16x16x32_f16 v[6:9], v[198:201], v[230:233], 0
	v_mfma_f32_16x16x32_f16 v[50:53], v[194:197], v[210:213], v[50:53]
	v_mfma_f32_16x16x32_f16 v[46:49], v[202:205], v[210:213], v[46:49]
	v_mfma_f32_16x16x32_f16 v[34:37], v[194:197], v[218:221], v[34:37]
	v_mfma_f32_16x16x32_f16 v[30:33], v[202:205], v[218:221], v[30:33]
	v_mfma_f32_16x16x32_f16 v[18:21], v[194:197], v[226:229], v[18:21]
	v_mfma_f32_16x16x32_f16 v[14:17], v[202:205], v[226:229], v[14:17]
	v_mfma_f32_16x16x32_f16 v[10:13], v[194:197], v[234:237], v[10:13]
	v_mfma_f32_16x16x32_f16 v[6:9], v[202:205], v[234:237], v[6:9]
	s_barrier
	s_add_i32 s48, 0, 0x18000
	v_add_u32_e32 v177, s48, v148
	s_add_i32 s49, 0, 0x1c000
	ds_read_b128 v[152:155], v177
	ds_read_b128 v[178:181], v177 offset:1024
	ds_read_b128 v[182:185], v177 offset:2048
	ds_read_b128 v[186:189], v177 offset:3072
	v_add_u32_e32 v177, s49, v148
	ds_read_b128 v[190:193], v177
	ds_read_b128 v[194:197], v177 offset:1024
	ds_read_b128 v[198:201], v177 offset:2048
	ds_read_b128 v[202:205], v177 offset:3072
	s_add_u32 s26, s26, 0x40000
	s_addc_u32 s27, s27, 0
	s_mov_b32 m0, s31
	v_lshl_add_u64 v[246:247], s[26:27], 0, v[138:139]
	ds_read_b128 v[206:209], v151 offset:32768
	ds_read_b128 v[210:213], v151 offset:33792
	ds_read_b128 v[214:217], v151 offset:34816
	ds_read_b128 v[218:221], v151 offset:35840
	ds_read_b128 v[222:225], v151 offset:36864
	ds_read_b128 v[226:229], v151 offset:37888
	ds_read_b128 v[230:233], v151 offset:38912
	ds_read_b128 v[234:237], v151 offset:39936
	global_load_lds_dwordx4 v[246:247], off
	v_lshl_add_u64 v[246:247], s[26:27], 0, v[134:135]
	s_mov_b32 m0, s38
	s_nop 0
	global_load_lds_dwordx4 v[246:247], off
	s_waitcnt vmcnt(8)
	s_waitcnt lgkmcnt(0)
	s_barrier
	s_waitcnt lgkmcnt(0)
	v_mfma_f32_16x16x32_f16 v[130:133], v[152:155], v[206:209], v[130:133]
	v_mfma_f32_16x16x32_f16 v[126:129], v[182:185], v[206:209], v[126:129]
	v_mfma_f32_16x16x32_f16 v[122:125], v[152:155], v[214:217], v[122:125]
	v_mfma_f32_16x16x32_f16 v[118:121], v[182:185], v[214:217], v[118:121]
	v_mfma_f32_16x16x32_f16 v[106:109], v[152:155], v[222:225], v[106:109]
	v_mfma_f32_16x16x32_f16 v[102:105], v[182:185], v[222:225], v[102:105]
	v_mfma_f32_16x16x32_f16 v[90:93], v[152:155], v[230:233], v[90:93]
	v_mfma_f32_16x16x32_f16 v[86:89], v[182:185], v[230:233], v[86:89]
	v_mfma_f32_16x16x32_f16 v[130:133], v[178:181], v[210:213], v[130:133]
	v_mfma_f32_16x16x32_f16 v[126:129], v[186:189], v[210:213], v[126:129]
	v_mfma_f32_16x16x32_f16 v[122:125], v[178:181], v[218:221], v[122:125]
	v_mfma_f32_16x16x32_f16 v[118:121], v[186:189], v[218:221], v[118:121]
	v_mfma_f32_16x16x32_f16 v[106:109], v[178:181], v[226:229], v[106:109]
	v_mfma_f32_16x16x32_f16 v[102:105], v[186:189], v[226:229], v[102:105]
	v_mfma_f32_16x16x32_f16 v[90:93], v[178:181], v[234:237], v[90:93]
	v_mfma_f32_16x16x32_f16 v[86:89], v[186:189], v[234:237], v[86:89]
	v_mfma_f32_16x16x32_f16 v[114:117], v[190:193], v[206:209], v[114:117]
	v_mfma_f32_16x16x32_f16 v[110:113], v[198:201], v[206:209], v[110:113]
	v_mfma_f32_16x16x32_f16 v[98:101], v[190:193], v[214:217], v[98:101]
	v_mfma_f32_16x16x32_f16 v[94:97], v[198:201], v[214:217], v[94:97]
	v_mfma_f32_16x16x32_f16 v[82:85], v[190:193], v[222:225], v[82:85]
	v_mfma_f32_16x16x32_f16 v[78:81], v[198:201], v[222:225], v[78:81]
	v_mfma_f32_16x16x32_f16 v[74:77], v[190:193], v[230:233], v[74:77]
	v_mfma_f32_16x16x32_f16 v[70:73], v[198:201], v[230:233], v[70:73]
	v_mfma_f32_16x16x32_f16 v[114:117], v[194:197], v[210:213], v[114:117]
	v_mfma_f32_16x16x32_f16 v[110:113], v[202:205], v[210:213], v[110:113]
	v_mfma_f32_16x16x32_f16 v[98:101], v[194:197], v[218:221], v[98:101]
	v_mfma_f32_16x16x32_f16 v[94:97], v[202:205], v[218:221], v[94:97]
	v_mfma_f32_16x16x32_f16 v[82:85], v[194:197], v[226:229], v[82:85]
	v_mfma_f32_16x16x32_f16 v[78:81], v[202:205], v[226:229], v[78:81]
	v_mfma_f32_16x16x32_f16 v[74:77], v[194:197], v[234:237], v[74:77]
	v_mfma_f32_16x16x32_f16 v[70:73], v[202:205], v[234:237], v[70:73]
	s_barrier
; #define STAGE(bufoff, gbase, voff) do { _Pragma("unroll") for (int _i = 0; _i < 2; ++_i) \
;     __builtin_amdgcn_global_load_lds((const unsigned*)((const char*)(gbase) + (voff)[_i]), (LAS unsigned*)(lds + (bufoff) + ldsw + _i * 8192), 16, 0, 0); } while (0)
; #define LDA(dst, b, h) do { _Pragma("unroll") for (int m = 0; m < 4; ++m) _Pragma("unroll") for (int k = 0; k < 2; ++k) dst[m][k] = *(const LAS half8*)(lds + SA(b, h) + aoff + m * 2048 + k * 1024); } while (0)
; #define LDB(dst, b, h) do { _Pragma("unroll") for (int n = 0; n < 2; ++n) _Pragma("unroll") for (int k = 0; k < 2; ++k) dst[n][k] = *(const LAS half8*)(lds + SB(b, h) + boff + n * 2048 + k * 1024); } while (0)
; #define MMA(ai, bj, At_, Bt_) do { __builtin_amdgcn_s_setprio(1); \
;     _Pragma("unroll") for (int m = 0; m < 4; ++m) _Pragma("unroll") for (int n = 0; n < 2; ++n) _Pragma("unroll") for (int k = 0; k < 2; ++k) \
;       acc[ai][bj][m][n] = MFMA16(Bt_[n][k], At_[m][k], acc[ai][bj][m][n]); \
;     __builtin_amdgcn_s_setprio(0); } while (0)
; #define WAIT_V(n) asm volatile("s_waitcnt vmcnt(" #n ")" ::: "memory")
; #define BAR __builtin_amdgcn_s_barrier()
; template <int EPI>
; DI void gemm_phase(const int wid_s, const h16* __restrict__ A, const h16* __restrict__ Bt, const int N, const int K, const EpiArgs ea) {
;     ...
;     for (int t = 0; t < nt; t += 2) {
;       const bool last = (t == nt - 2);
;       const char* a1 = cA + (size_t)(t + 1) * kstep;
;       const char* a2 = last ? nA : cA + (size_t)(t + 2) * kstep; const char* b2 = last ? nB : cB + (size_t)(t + 2) * kstep;
;       const char* a3 = a2 + kstep; const char* b3 = b2 + kstep;
;       LDB(B0, 0, 0); LDB(B1, 0, 1); SCHED; LDA(At, 0, 0); STAGE(SA(1, 1), a1 + hstep, voffA);
;       WAIT_V(8); WAIT_L(0); BAR; MMA(0, 0, At, B0); MMA(0, 1, At, B1); BAR; SCHED;
;       LDA(At, 0, 1); STAGE(SB(0, 0), b2, voffB); STAGE(SB(0, 1), b2 + hstep, voffB); STAGE(SA(0, 0), a2, voffA);
;       WAIT_V(8); WAIT_L(0); BAR; MMA(1, 0, At, B0); MMA(1, 1, At, B1); BAR; SCHED;
;       LDB(B0, 1, 0); LDB(B1, 1, 1); SCHED; LDA(At, 1, 0); STAGE(SA(0, 1), a2 + hstep, voffA);
;       WAIT_V(8); WAIT_L(0); BAR; MMA(0, 0, At, B0); MMA(0, 1, At, B1); BAR; SCHED;
;       LDA(At, 1, 1); STAGE(SB(1, 0), b3, voffB); STAGE(SB(1, 1), b3 + hstep, voffB); STAGE(SA(1, 0), a3, voffA);
;       WAIT_V(8); WAIT_L(0); BAR; MMA(1, 0, At, B0); MMA(1, 1, At, B1); BAR; SCHED;
	s_add_i32 s26, s48, s30
	v_lshl_add_u64 v[238:239], v[238:239], 0, s[36:37]
	s_mov_b32 m0, s26
	ds_read_b128 v[206:209], v151 offset:49152
	ds_read_b128 v[210:213], v151 offset:50176
	ds_read_b128 v[214:217], v151 offset:51200
	ds_read_b128 v[218:221], v151 offset:52224
	ds_read_b128 v[222:225], v151 offset:53248
	ds_read_b128 v[226:229], v151 offset:54272
	ds_read_b128 v[230:233], v151 offset:55296
	ds_read_b128 v[234:237], v151 offset:56320
	global_load_lds_dwordx4 v[238:239], off
	s_add_i32 m0, s26, 0x2000
	s_add_u32 s22, s22, 0x40080
	v_lshl_add_u64 v[238:239], v[240:241], 0, s[36:37]
	s_addc_u32 s23, s23, 0
	s_add_i32 s26, s49, s30
	global_load_lds_dwordx4 v[238:239], off
	v_lshl_add_u64 v[238:239], s[22:23], 0, v[0:1]
	s_mov_b32 m0, s26
	s_nop 0
	global_load_lds_dwordx4 v[238:239], off
	v_lshl_add_u64 v[238:239], s[22:23], 0, v[2:3]
	s_add_i32 m0, s26, 0x2000
	s_nop 0
	global_load_lds_dwordx4 v[238:239], off
	v_lshl_add_u64 v[238:239], v[242:243], 0, s[36:37]
	s_mov_b32 m0, s39
	s_nop 0
	global_load_lds_dwordx4 v[238:239], off
	v_lshl_add_u64 v[238:239], v[244:245], 0, s[36:37]
	s_mov_b32 m0, s40
	s_nop 0
	global_load_lds_dwordx4 v[238:239], off
	s_waitcnt vmcnt(8)
	s_waitcnt lgkmcnt(0)
	s_barrier
	s_waitcnt lgkmcnt(0)
	v_mfma_f32_16x16x32_f16 v[66:69], v[152:155], v[206:209], v[66:69]
	v_mfma_f32_16x16x32_f16 v[62:65], v[182:185], v[206:209], v[62:65]
	v_mfma_f32_16x16x32_f16 v[58:61], v[152:155], v[214:217], v[58:61]
	v_mfma_f32_16x16x32_f16 v[54:57], v[182:185], v[214:217], v[54:57]
	v_mfma_f32_16x16x32_f16 v[42:45], v[152:155], v[222:225], v[42:45]
	v_mfma_f32_16x16x32_f16 v[38:41], v[182:185], v[222:225], v[38:41]
	v_mfma_f32_16x16x32_f16 v[26:29], v[152:155], v[230:233], v[26:29]
	v_mfma_f32_16x16x32_f16 v[22:25], v[182:185], v[230:233], v[22:25]
	v_mfma_f32_16x16x32_f16 v[66:69], v[178:181], v[210:213], v[66:69]
	v_mfma_f32_16x16x32_f16 v[62:65], v[186:189], v[210:213], v[62:65]
	v_mfma_f32_16x16x32_f16 v[58:61], v[178:181], v[218:221], v[58:61]
	v_mfma_f32_16x16x32_f16 v[54:57], v[186:189], v[218:221], v[54:57]
	v_mfma_f32_16x16x32_f16 v[42:45], v[178:181], v[226:229], v[42:45]
	v_mfma_f32_16x16x32_f16 v[38:41], v[186:189], v[226:229], v[38:41]
	v_mfma_f32_16x16x32_f16 v[26:29], v[178:181], v[234:237], v[26:29]
	v_mfma_f32_16x16x32_f16 v[22:25], v[186:189], v[234:237], v[22:25]
	v_mfma_f32_16x16x32_f16 v[50:53], v[190:193], v[206:209], v[50:53]
	v_mfma_f32_16x16x32_f16 v[46:49], v[198:201], v[206:209], v[46:49]
	v_mfma_f32_16x16x32_f16 v[34:37], v[190:193], v[214:217], v[34:37]
	v_mfma_f32_16x16x32_f16 v[30:33], v[198:201], v[214:217], v[30:33]
	v_mfma_f32_16x16x32_f16 v[18:21], v[190:193], v[222:225], v[18:21]
	v_mfma_f32_16x16x32_f16 v[14:17], v[198:201], v[222:225], v[14:17]
	v_mfma_f32_16x16x32_f16 v[10:13], v[190:193], v[230:233], v[10:13]
	v_mfma_f32_16x16x32_f16 v[6:9], v[198:201], v[230:233], v[6:9]
	v_mfma_f32_16x16x32_f16 v[50:53], v[194:197], v[210:213], v[50:53]
	v_mfma_f32_16x16x32_f16 v[46:49], v[202:205], v[210:213], v[46:49]
	v_mfma_f32_16x16x32_f16 v[34:37], v[194:197], v[218:221], v[34:37]
	v_mfma_f32_16x16x32_f16 v[30:33], v[202:205], v[218:221], v[30:33]
	v_mfma_f32_16x16x32_f16 v[18:21], v[194:197], v[226:229], v[18:21]
	v_mfma_f32_16x16x32_f16 v[14:17], v[202:205], v[226:229], v[14:17]
	v_mfma_f32_16x16x32_f16 v[10:13], v[194:197], v[234:237], v[10:13]
	v_mfma_f32_16x16x32_f16 v[6:9], v[202:205], v[234:237], v[6:9]
	s_barrier
	s_add_i32 s47, s47, 2
	s_add_u32 s20, s20, 0x100
	s_addc_u32 s21, s21, 0
	s_cmp_gt_u32 s47, 13
